# baseline (speedup 1.0000x reference)
; #define PG8_STAGE(bufoff, gbase, voff) do { _Pragma("unroll") for (int _i = 0; _i < 2; ++_i) \
;         __builtin_amdgcn_global_load_lds((const unsigned*)((const char*)(gbase) + (voff)[_i]), (PG8_LAS unsigned*)(lds + (bufoff) + ldsw + _i * 8192), 16, 0, 0); } while (0)
; #define PG8_LDA(dst, b, h) do { _Pragma("unroll") for (int m = 0; m < 4; ++m) _Pragma("unroll") for (int k = 0; k < 2; ++k) dst[m][k] = *(const PG8_LAS bf16x8*)(lds + PG8_SA(b, h) + aoff + m * 2048 + k * 1024); } while (0)
; #define PG8_LDB(dst, b, h) do { _Pragma("unroll") for (int n = 0; n < 2; ++n) _Pragma("unroll") for (int k = 0; k < 2; ++k) dst[n][k] = *(const PG8_LAS bf16x8*)(lds + PG8_SB(b, h) + boff + n * 2048 + k * 1024); } while (0)
; #define PG8_MMA(ai, bj, At, Bt) do { __builtin_amdgcn_s_setprio(1); _Pragma("unroll") for (int m = 0; m < 4; ++m) _Pragma("unroll") for (int n = 0; n < 2; ++n) _Pragma("unroll") for (int k = 0; k < 2; ++k) \
;         acc[ai][bj][m][n] = __builtin_amdgcn_mfma_f32_16x16x32_bf16(Bt[n][k], At[m][k], acc[ai][bj][m][n], 0, 0, 0); __builtin_amdgcn_s_setprio(0); } while (0)
; #define PG8_WAIT_V(n) asm volatile("s_waitcnt vmcnt(" #n ")" ::: "memory")
; #define PG8_WAIT_L(n) asm volatile("s_waitcnt lgkmcnt(" #n ")" ::: "memory")
; #define PG8_BAR __builtin_amdgcn_s_barrier()
; #define PG8_SCHED __builtin_amdgcn_sched_barrier(0)
; template <class Epi, class Sched, bool ALIGN_EPI = false, bool SP2 = false>
; __device__ __forceinline__ void gemm_phase(PG8_LAS unsigned char* lds, const Gemm g, const Sched& S, const Epi& E) {
;     ...
;             if constexpr (SP2) {
;             PG8_LDB(B0, 0, 0); PG8_LDB(B1, 0, 1); PG8_SCHED; PG8_LDA(At, 0, 0); PG8_STAGE(PG8_SA(1, 1), a1 + hstepA, voffA);
;             PG8_WAIT_V(8); PG8_WAIT_L(0); PG8_BAR; PG8_MMA(0, 0, At, B0); PG8_MMA(0, 1, At, B1); PG8_BAR; PG8_SCHED;
;             PG8_LDA(At, 0, 1); PG8_STAGE(PG8_SB(0, 0), b2, voffB); PG8_STAGE(PG8_SB(0, 1), b2 + hstep, voffB); PG8_STAGE(PG8_SA(0, 0), a2, voffA);
;             PG8_WAIT_V(8); PG8_WAIT_L(0); PG8_BAR; PG8_MMA(1, 0, At, B0); PG8_MMA(1, 1, At, B1); PG8_BAR; PG8_SCHED;
.Lpe_noe:
	s_waitcnt vmcnt(24)
	s_waitcnt lgkmcnt(0)
	s_barrier
	s_setprio 1
	v_mfma_f32_16x16x32_bf16 v[126:129], v[130:133], v[198:201], 0
	v_mfma_f32_16x16x32_bf16 v[122:125], v[138:141], v[198:201], 0
	v_mfma_f32_16x16x32_bf16 v[110:113], v[130:133], v[206:209], 0
	v_mfma_f32_16x16x32_bf16 v[106:109], v[138:141], v[206:209], 0
	v_mfma_f32_16x16x32_bf16 v[94:97], v[130:133], v[214:217], 0
	v_mfma_f32_16x16x32_bf16 v[90:93], v[138:141], v[214:217], 0
	v_mfma_f32_16x16x32_bf16 v[78:81], v[130:133], v[222:225], 0
	v_mfma_f32_16x16x32_bf16 v[74:77], v[138:141], v[222:225], 0
	v_mfma_f32_16x16x32_bf16 v[126:129], v[134:137], v[202:205], v[126:129]
	v_mfma_f32_16x16x32_bf16 v[122:125], v[142:145], v[202:205], v[122:125]
	v_mfma_f32_16x16x32_bf16 v[110:113], v[134:137], v[210:213], v[110:113]
	v_mfma_f32_16x16x32_bf16 v[106:109], v[142:145], v[210:213], v[106:109]
	v_mfma_f32_16x16x32_bf16 v[94:97], v[134:137], v[218:221], v[94:97]
	v_mfma_f32_16x16x32_bf16 v[90:93], v[142:145], v[218:221], v[90:93]
	v_mfma_f32_16x16x32_bf16 v[78:81], v[134:137], v[226:229], v[78:81]
	v_mfma_f32_16x16x32_bf16 v[74:77], v[142:145], v[226:229], v[74:77]
	v_mfma_f32_16x16x32_bf16 v[118:121], v[146:149], v[198:201], 0
	v_mfma_f32_16x16x32_bf16 v[114:117], v[190:193], v[198:201], 0
	v_mfma_f32_16x16x32_bf16 v[102:105], v[146:149], v[206:209], 0
	v_mfma_f32_16x16x32_bf16 v[98:101], v[190:193], v[206:209], 0
	v_mfma_f32_16x16x32_bf16 v[86:89], v[146:149], v[214:217], 0
	v_mfma_f32_16x16x32_bf16 v[82:85], v[190:193], v[214:217], 0
	v_mfma_f32_16x16x32_bf16 v[70:73], v[146:149], v[222:225], 0
	v_mfma_f32_16x16x32_bf16 v[66:69], v[190:193], v[222:225], 0
	v_mfma_f32_16x16x32_bf16 v[118:121], v[170:173], v[202:205], v[118:121]
	v_mfma_f32_16x16x32_bf16 v[114:117], v[194:197], v[202:205], v[114:117]
	v_mfma_f32_16x16x32_bf16 v[102:105], v[170:173], v[210:213], v[102:105]
	v_mfma_f32_16x16x32_bf16 v[98:101], v[194:197], v[210:213], v[98:101]
	v_mfma_f32_16x16x32_bf16 v[86:89], v[170:173], v[218:221], v[86:89]
	v_mfma_f32_16x16x32_bf16 v[82:85], v[194:197], v[218:221], v[82:85]
	v_mfma_f32_16x16x32_bf16 v[70:73], v[170:173], v[226:229], v[70:73]
	v_mfma_f32_16x16x32_bf16 v[66:69], v[194:197], v[226:229], v[66:69]
	s_setprio 0
	s_barrier
	s_add_i32 s94, s94, s16
	v_lshl_add_u64 v[150:151], s[12:13], 0, v[156:157]
	s_mov_b32 m0, s94
	ds_read_b128 v[198:201], v186 offset:16384
	ds_read_b128 v[202:205], v186 offset:17408
	ds_read_b128 v[206:209], v186 offset:18432
	ds_read_b128 v[210:213], v186 offset:19456
	ds_read_b128 v[214:217], v186 offset:20480
	ds_read_b128 v[218:221], v186 offset:21504
	ds_read_b128 v[222:225], v186 offset:22528
	ds_read_b128 v[226:229], v186 offset:23552
	global_load_lds_dwordx4 v[150:151], off
	s_add_i32 m0, s94, 0x2000
	s_add_u32 s94, s12, 0x40000
	v_lshl_add_u64 v[166:167], s[12:13], 0, v[160:161]
	s_addc_u32 s95, s13, 0
	s_add_i32 vcc_hi, vcc_hi, s16
	global_load_lds_dwordx4 v[166:167], off
	v_lshl_add_u64 v[230:231], s[94:95], 0, v[156:157]
	s_mov_b32 m0, vcc_hi
	v_lshl_add_u64 v[232:233], s[44:45], 0, v[158:159]
	global_load_lds_dwordx4 v[230:231], off
	v_lshl_add_u64 v[230:231], s[94:95], 0, v[160:161]
	s_add_i32 m0, vcc_hi, 0x2000
	s_nop 0
	global_load_lds_dwordx4 v[230:231], off
	v_lshl_add_u64 v[230:231], s[44:45], 0, v[154:155]
	s_mov_b32 m0, s17
	s_nop 0
	global_load_lds_dwordx4 v[230:231], off
	s_mov_b32 m0, s51
	s_nop 0
	global_load_lds_dwordx4 v[232:233], off
	s_cmp_eq_u32 s87, 1
	s_cbranch_scc1 .Lpe_w2_strict
	s_waitcnt vmcnt(24)
	s_branch .Lpe_w2_done

; #define PG8_STAGE(bufoff, gbase, voff) do { _Pragma("unroll") for (int _i = 0; _i < 2; ++_i) \
;         __builtin_amdgcn_global_load_lds((const unsigned*)((const char*)(gbase) + (voff)[_i]), (PG8_LAS unsigned*)(lds + (bufoff) + ldsw + _i * 8192), 16, 0, 0); } while (0)
; #define PG8_LDA(dst, b, h) do { _Pragma("unroll") for (int m = 0; m < 4; ++m) _Pragma("unroll") for (int k = 0; k < 2; ++k) dst[m][k] = *(const PG8_LAS bf16x8*)(lds + PG8_SA(b, h) + aoff + m * 2048 + k * 1024); } while (0)
; #define PG8_LDB(dst, b, h) do { _Pragma("unroll") for (int n = 0; n < 2; ++n) _Pragma("unroll") for (int k = 0; k < 2; ++k) dst[n][k] = *(const PG8_LAS bf16x8*)(lds + PG8_SB(b, h) + boff + n * 2048 + k * 1024); } while (0)
; #define PG8_MMA(ai, bj, At, Bt) do { __builtin_amdgcn_s_setprio(1); _Pragma("unroll") for (int m = 0; m < 4; ++m) _Pragma("unroll") for (int n = 0; n < 2; ++n) _Pragma("unroll") for (int k = 0; k < 2; ++k) \
;         acc[ai][bj][m][n] = __builtin_amdgcn_mfma_f32_16x16x32_bf16(Bt[n][k], At[m][k], acc[ai][bj][m][n], 0, 0, 0); __builtin_amdgcn_s_setprio(0); } while (0)
; #define PG8_WAIT_V(n) asm volatile("s_waitcnt vmcnt(" #n ")" ::: "memory")
; #define PG8_WAIT_L(n) asm volatile("s_waitcnt lgkmcnt(" #n ")" ::: "memory")
; #define PG8_BAR __builtin_amdgcn_s_barrier()
; #define PG8_SCHED __builtin_amdgcn_sched_barrier(0)
; template <class Epi, class Sched, bool ALIGN_EPI = false, bool SP2 = false>
; __device__ __forceinline__ void gemm_phase(PG8_LAS unsigned char* lds, const Gemm g, const Sched& S, const Epi& E) {
;     ...
;             PG8_WAIT_V(8); PG8_WAIT_L(0); PG8_BAR; PG8_MMA(1, 0, At, B0); PG8_MMA(1, 1, At, B1); PG8_BAR; PG8_SCHED;
;             PG8_LDB(B0, 1, 0); PG8_LDB(B1, 1, 1); PG8_SCHED; PG8_LDA(At, 1, 0); PG8_STAGE(PG8_SA(0, 1), a2 + hstepA, voffA);
;             PG8_WAIT_V(8); PG8_WAIT_L(0); PG8_BAR; PG8_MMA(0, 0, At, B0); PG8_MMA(0, 1, At, B1); PG8_BAR; PG8_SCHED;
.Lpe_w2_done:
	s_waitcnt lgkmcnt(0)
	s_barrier
	s_setprio 1
	v_mfma_f32_16x16x32_bf16 v[62:65], v[130:133], v[198:201], 0
	v_mfma_f32_16x16x32_bf16 v[58:61], v[138:141], v[198:201], 0
	v_mfma_f32_16x16x32_bf16 v[46:49], v[130:133], v[206:209], 0
	v_mfma_f32_16x16x32_bf16 v[42:45], v[138:141], v[206:209], 0
	v_mfma_f32_16x16x32_bf16 v[30:33], v[130:133], v[214:217], 0
	v_mfma_f32_16x16x32_bf16 v[26:29], v[138:141], v[214:217], 0
	v_mfma_f32_16x16x32_bf16 v[14:17], v[130:133], v[222:225], 0
	v_mfma_f32_16x16x32_bf16 v[10:13], v[138:141], v[222:225], 0
	v_mfma_f32_16x16x32_bf16 v[62:65], v[134:137], v[202:205], v[62:65]
	v_mfma_f32_16x16x32_bf16 v[58:61], v[142:145], v[202:205], v[58:61]
	v_mfma_f32_16x16x32_bf16 v[46:49], v[134:137], v[210:213], v[46:49]
	v_mfma_f32_16x16x32_bf16 v[42:45], v[142:145], v[210:213], v[42:45]
	v_mfma_f32_16x16x32_bf16 v[30:33], v[134:137], v[218:221], v[30:33]
	v_mfma_f32_16x16x32_bf16 v[26:29], v[142:145], v[218:221], v[26:29]
	v_mfma_f32_16x16x32_bf16 v[14:17], v[134:137], v[226:229], v[14:17]
	v_mfma_f32_16x16x32_bf16 v[10:13], v[142:145], v[226:229], v[10:13]
	v_mfma_f32_16x16x32_bf16 v[54:57], v[146:149], v[198:201], 0
	v_mfma_f32_16x16x32_bf16 v[50:53], v[190:193], v[198:201], 0
	v_mfma_f32_16x16x32_bf16 v[38:41], v[146:149], v[206:209], 0
	v_mfma_f32_16x16x32_bf16 v[34:37], v[190:193], v[206:209], 0
	v_mfma_f32_16x16x32_bf16 v[22:25], v[146:149], v[214:217], 0
	v_mfma_f32_16x16x32_bf16 v[18:21], v[190:193], v[214:217], 0
	v_mfma_f32_16x16x32_bf16 v[6:9], v[146:149], v[222:225], 0
	v_mfma_f32_16x16x32_bf16 v[2:5], v[190:193], v[222:225], 0
	v_mfma_f32_16x16x32_bf16 v[54:57], v[170:173], v[202:205], v[54:57]
	v_mfma_f32_16x16x32_bf16 v[50:53], v[194:197], v[202:205], v[50:53]
	v_mfma_f32_16x16x32_bf16 v[38:41], v[170:173], v[210:213], v[38:41]
	v_mfma_f32_16x16x32_bf16 v[34:37], v[194:197], v[210:213], v[34:37]
	v_mfma_f32_16x16x32_bf16 v[22:25], v[170:173], v[218:221], v[22:25]
	v_mfma_f32_16x16x32_bf16 v[18:21], v[194:197], v[218:221], v[18:21]
	v_mfma_f32_16x16x32_bf16 v[6:9], v[170:173], v[226:229], v[6:9]
	v_mfma_f32_16x16x32_bf16 v[2:5], v[194:197], v[226:229], v[2:5]
	s_setprio 0
	s_barrier
	s_add_i32 s94, 0, 0x18000
	v_add_u32_e32 v0, s94, v179
	s_add_i32 s95, 0, 0x1c000
	ds_read_b128 v[130:133], v0
	ds_read_b128 v[134:137], v0 offset:1024
	ds_read_b128 v[138:141], v0 offset:2048
	ds_read_b128 v[142:145], v0 offset:3072
	v_add_u32_e32 v0, s95, v179
	ds_read_b128 v[146:149], v0
	ds_read_b128 v[170:173], v0 offset:1024
	ds_read_b128 v[190:193], v0 offset:2048
	ds_read_b128 v[194:197], v0 offset:3072
	s_add_u32 s44, s44, 0x40000
	s_addc_u32 s45, s45, 0
	s_mov_b32 m0, s35
	v_lshl_add_u64 v[234:235], s[44:45], 0, v[154:155]
	ds_read_b128 v[198:201], v186 offset:32768
	ds_read_b128 v[202:205], v186 offset:33792
	ds_read_b128 v[206:209], v186 offset:34816
	ds_read_b128 v[210:213], v186 offset:35840
	ds_read_b128 v[214:217], v186 offset:36864
	ds_read_b128 v[218:221], v186 offset:37888
	ds_read_b128 v[222:225], v186 offset:38912
	ds_read_b128 v[226:229], v186 offset:39936
	global_load_lds_dwordx4 v[234:235], off
	v_lshl_add_u64 v[234:235], s[44:45], 0, v[158:159]
	s_mov_b32 m0, s30
	s_nop 0
	global_load_lds_dwordx4 v[234:235], off
	s_cmp_eq_u32 s87, 1
	s_cbranch_scc1 .Lpe_w3_strict
	s_waitcnt vmcnt(24)
	s_branch .Lpe_w3_done

; #define PG8_STAGE(bufoff, gbase, voff) do { _Pragma("unroll") for (int _i = 0; _i < 2; ++_i) \
;         __builtin_amdgcn_global_load_lds((const unsigned*)((const char*)(gbase) + (voff)[_i]), (PG8_LAS unsigned*)(lds + (bufoff) + ldsw + _i * 8192), 16, 0, 0); } while (0)
; #define PG8_LDA(dst, b, h) do { _Pragma("unroll") for (int m = 0; m < 4; ++m) _Pragma("unroll") for (int k = 0; k < 2; ++k) dst[m][k] = *(const PG8_LAS bf16x8*)(lds + PG8_SA(b, h) + aoff + m * 2048 + k * 1024); } while (0)
; #define PG8_MMA(ai, bj, At, Bt) do { __builtin_amdgcn_s_setprio(1); _Pragma("unroll") for (int m = 0; m < 4; ++m) _Pragma("unroll") for (int n = 0; n < 2; ++n) _Pragma("unroll") for (int k = 0; k < 2; ++k) \
;         acc[ai][bj][m][n] = __builtin_amdgcn_mfma_f32_16x16x32_bf16(Bt[n][k], At[m][k], acc[ai][bj][m][n], 0, 0, 0); __builtin_amdgcn_s_setprio(0); } while (0)
; #define PG8_WAIT_V(n) asm volatile("s_waitcnt vmcnt(" #n ")" ::: "memory")
; #define PG8_WAIT_L(n) asm volatile("s_waitcnt lgkmcnt(" #n ")" ::: "memory")
; #define PG8_BAR __builtin_amdgcn_s_barrier()
; #define PG8_SCHED __builtin_amdgcn_sched_barrier(0)
; template <class Epi, class Sched, bool ALIGN_EPI = false, bool SP2 = false>
; __device__ __forceinline__ void gemm_phase(PG8_LAS unsigned char* lds, const Gemm g, const Sched& S, const Epi& E) {
;     ...
;         for (int t = 0; t < nt; t += 2) {
;             if constexpr (Epi::MIDSCALE) { if (t == (nt >> 1)) E.midscale(acc, cur, wr, fr, ui); }
;             const bool last = (t == nt - 2);
;             const char* a1 = cA + (size_t)(t >> 1) * apair + kstep;
;             const char* a2 = last ? nA : cA + (size_t)((t >> 1) + 1) * apair; const char* b2 = last ? nB : cB + (size_t)(t + 2) * kstep;
;     ...
;             PG8_WAIT_V(8); PG8_WAIT_L(0); PG8_BAR; PG8_MMA(0, 0, At, B0); PG8_MMA(0, 1, At, B1); PG8_BAR; PG8_SCHED;
;             PG8_LDA(At, 1, 1); PG8_STAGE(PG8_SB(1, 0), b3, voffB); PG8_STAGE(PG8_SB(1, 1), b3 + hstep, voffB); PG8_STAGE(PG8_SA(1, 0), a3, voffA);
;             PG8_WAIT_V(8); PG8_WAIT_L(0); PG8_BAR; PG8_MMA(1, 0, At, B0); PG8_MMA(1, 1, At, B1); PG8_BAR; PG8_SCHED;
.Lpe_w3_done:
	s_waitcnt lgkmcnt(0)
	s_barrier
	s_setprio 1
	v_mfma_f32_16x16x32_bf16 v[126:129], v[130:133], v[198:201], v[126:129]
	v_mfma_f32_16x16x32_bf16 v[122:125], v[138:141], v[198:201], v[122:125]
	v_mfma_f32_16x16x32_bf16 v[110:113], v[130:133], v[206:209], v[110:113]
	v_mfma_f32_16x16x32_bf16 v[106:109], v[138:141], v[206:209], v[106:109]
	v_mfma_f32_16x16x32_bf16 v[94:97], v[130:133], v[214:217], v[94:97]
	v_mfma_f32_16x16x32_bf16 v[90:93], v[138:141], v[214:217], v[90:93]
	v_mfma_f32_16x16x32_bf16 v[78:81], v[130:133], v[222:225], v[78:81]
	v_mfma_f32_16x16x32_bf16 v[74:77], v[138:141], v[222:225], v[74:77]
	v_mfma_f32_16x16x32_bf16 v[126:129], v[134:137], v[202:205], v[126:129]
	v_mfma_f32_16x16x32_bf16 v[122:125], v[142:145], v[202:205], v[122:125]
	v_mfma_f32_16x16x32_bf16 v[110:113], v[134:137], v[210:213], v[110:113]
	v_mfma_f32_16x16x32_bf16 v[106:109], v[142:145], v[210:213], v[106:109]
	v_mfma_f32_16x16x32_bf16 v[94:97], v[134:137], v[218:221], v[94:97]
	v_mfma_f32_16x16x32_bf16 v[90:93], v[142:145], v[218:221], v[90:93]
	v_mfma_f32_16x16x32_bf16 v[78:81], v[134:137], v[226:229], v[78:81]
	v_mfma_f32_16x16x32_bf16 v[74:77], v[142:145], v[226:229], v[74:77]
	v_mfma_f32_16x16x32_bf16 v[118:121], v[146:149], v[198:201], v[118:121]
	v_mfma_f32_16x16x32_bf16 v[114:117], v[190:193], v[198:201], v[114:117]
	v_mfma_f32_16x16x32_bf16 v[102:105], v[146:149], v[206:209], v[102:105]
	v_mfma_f32_16x16x32_bf16 v[98:101], v[190:193], v[206:209], v[98:101]
	v_mfma_f32_16x16x32_bf16 v[86:89], v[146:149], v[214:217], v[86:89]
	v_mfma_f32_16x16x32_bf16 v[82:85], v[190:193], v[214:217], v[82:85]
	v_mfma_f32_16x16x32_bf16 v[70:73], v[146:149], v[222:225], v[70:73]
	v_mfma_f32_16x16x32_bf16 v[66:69], v[190:193], v[222:225], v[66:69]
	v_mfma_f32_16x16x32_bf16 v[118:121], v[170:173], v[202:205], v[118:121]
	v_mfma_f32_16x16x32_bf16 v[114:117], v[194:197], v[202:205], v[114:117]
	v_mfma_f32_16x16x32_bf16 v[102:105], v[170:173], v[210:213], v[102:105]
	v_mfma_f32_16x16x32_bf16 v[98:101], v[194:197], v[210:213], v[98:101]
	v_mfma_f32_16x16x32_bf16 v[86:89], v[170:173], v[218:221], v[86:89]
	v_mfma_f32_16x16x32_bf16 v[82:85], v[194:197], v[218:221], v[82:85]
	v_mfma_f32_16x16x32_bf16 v[70:73], v[170:173], v[226:229], v[70:73]
	v_mfma_f32_16x16x32_bf16 v[66:69], v[194:197], v[226:229], v[66:69]
	s_setprio 0
	s_barrier
	s_add_i32 s44, s94, s16
	v_lshl_add_u64 v[150:151], v[150:151], 0, s[48:49]
	s_mov_b32 m0, s44
	ds_read_b128 v[198:201], v186 offset:49152
	ds_read_b128 v[202:205], v186 offset:50176
	ds_read_b128 v[206:209], v186 offset:51200
	ds_read_b128 v[210:213], v186 offset:52224
	ds_read_b128 v[214:217], v186 offset:53248
	ds_read_b128 v[218:221], v186 offset:54272
	ds_read_b128 v[222:225], v186 offset:55296
	ds_read_b128 v[226:229], v186 offset:56320
	global_load_lds_dwordx4 v[150:151], off
	s_add_i32 m0, s44, 0x2000
	s_add_u32 s12, s12, 0x40080
	v_lshl_add_u64 v[150:151], v[166:167], 0, s[48:49]
	s_addc_u32 s13, s13, 0
	s_add_i32 s44, s95, s16
	global_load_lds_dwordx4 v[150:151], off
	v_lshl_add_u64 v[150:151], s[12:13], 0, v[156:157]
	s_mov_b32 m0, s44
	s_nop 0
	global_load_lds_dwordx4 v[150:151], off
	v_lshl_add_u64 v[150:151], s[12:13], 0, v[160:161]
	s_add_i32 m0, s44, 0x2000
	s_nop 0
	global_load_lds_dwordx4 v[150:151], off
	v_lshl_add_u64 v[150:151], v[230:231], 0, s[48:49]
	s_mov_b32 m0, s59
	s_nop 0
	global_load_lds_dwordx4 v[150:151], off
	v_lshl_add_u64 v[150:151], v[232:233], 0, s[48:49]
	s_mov_b32 m0, s86
	s_nop 0
	global_load_lds_dwordx4 v[150:151], off
	s_waitcnt vmcnt(8)
	s_waitcnt lgkmcnt(0)
	s_barrier
	s_setprio 1
	v_mfma_f32_16x16x32_bf16 v[62:65], v[130:133], v[198:201], v[62:65]
	v_mfma_f32_16x16x32_bf16 v[58:61], v[138:141], v[198:201], v[58:61]
	v_mfma_f32_16x16x32_bf16 v[46:49], v[130:133], v[206:209], v[46:49]
	v_mfma_f32_16x16x32_bf16 v[42:45], v[138:141], v[206:209], v[42:45]
	v_mfma_f32_16x16x32_bf16 v[30:33], v[130:133], v[214:217], v[30:33]
	v_mfma_f32_16x16x32_bf16 v[26:29], v[138:141], v[214:217], v[26:29]
	v_mfma_f32_16x16x32_bf16 v[14:17], v[130:133], v[222:225], v[14:17]
	v_mfma_f32_16x16x32_bf16 v[10:13], v[138:141], v[222:225], v[10:13]
	v_mfma_f32_16x16x32_bf16 v[62:65], v[134:137], v[202:205], v[62:65]
	v_mfma_f32_16x16x32_bf16 v[58:61], v[142:145], v[202:205], v[58:61]
	v_mfma_f32_16x16x32_bf16 v[46:49], v[134:137], v[210:213], v[46:49]
	v_mfma_f32_16x16x32_bf16 v[42:45], v[142:145], v[210:213], v[42:45]
	v_mfma_f32_16x16x32_bf16 v[30:33], v[134:137], v[218:221], v[30:33]
	v_mfma_f32_16x16x32_bf16 v[26:29], v[142:145], v[218:221], v[26:29]
	v_mfma_f32_16x16x32_bf16 v[14:17], v[134:137], v[226:229], v[14:17]
	v_mfma_f32_16x16x32_bf16 v[10:13], v[142:145], v[226:229], v[10:13]
	v_mfma_f32_16x16x32_bf16 v[54:57], v[146:149], v[198:201], v[54:57]
	v_mfma_f32_16x16x32_bf16 v[50:53], v[190:193], v[198:201], v[50:53]
	v_mfma_f32_16x16x32_bf16 v[38:41], v[146:149], v[206:209], v[38:41]
	v_mfma_f32_16x16x32_bf16 v[34:37], v[190:193], v[206:209], v[34:37]
	v_mfma_f32_16x16x32_bf16 v[22:25], v[146:149], v[214:217], v[22:25]
	v_mfma_f32_16x16x32_bf16 v[18:21], v[190:193], v[214:217], v[18:21]
	v_mfma_f32_16x16x32_bf16 v[6:9], v[146:149], v[222:225], v[6:9]
	v_mfma_f32_16x16x32_bf16 v[2:5], v[190:193], v[222:225], v[2:5]
	v_mfma_f32_16x16x32_bf16 v[54:57], v[170:173], v[202:205], v[54:57]
	v_mfma_f32_16x16x32_bf16 v[50:53], v[194:197], v[202:205], v[50:53]
	v_mfma_f32_16x16x32_bf16 v[38:41], v[170:173], v[210:213], v[38:41]
	v_mfma_f32_16x16x32_bf16 v[34:37], v[194:197], v[210:213], v[34:37]
	v_mfma_f32_16x16x32_bf16 v[22:25], v[170:173], v[218:221], v[22:25]
	v_mfma_f32_16x16x32_bf16 v[18:21], v[194:197], v[218:221], v[18:21]
	v_mfma_f32_16x16x32_bf16 v[6:9], v[170:173], v[226:229], v[6:9]
	v_mfma_f32_16x16x32_bf16 v[2:5], v[194:197], v[226:229], v[2:5]
	s_setprio 0
	s_barrier
	s_add_i32 vcc_lo, vcc_lo, 2
	s_add_u32 s10, s10, 0x100
	s_addc_u32 s11, s11, 0
	s_add_u32 s47, s47, 0x100
	s_addc_u32 s63, s63, 0
; #define PG8_STAGE(bufoff, gbase, voff) do { _Pragma("unroll") for (int _i = 0; _i < 2; ++_i) \
;         __builtin_amdgcn_global_load_lds((const unsigned*)((const char*)(gbase) + (voff)[_i]), (PG8_LAS unsigned*)(lds + (bufoff) + ldsw + _i * 8192), 16, 0, 0); } while (0)
; #define PG8_LDA(dst, b, h) do { _Pragma("unroll") for (int m = 0; m < 4; ++m) _Pragma("unroll") for (int k = 0; k < 2; ++k) dst[m][k] = *(const PG8_LAS bf16x8*)(lds + PG8_SA(b, h) + aoff + m * 2048 + k * 1024); } while (0)
; #define PG8_LDB(dst, b, h) do { _Pragma("unroll") for (int n = 0; n < 2; ++n) _Pragma("unroll") for (int k = 0; k < 2; ++k) dst[n][k] = *(const PG8_LAS bf16x8*)(lds + PG8_SB(b, h) + boff + n * 2048 + k * 1024); } while (0)
; #define PG8_MMA(ai, bj, At, Bt) do { __builtin_amdgcn_s_setprio(1); _Pragma("unroll") for (int m = 0; m < 4; ++m) _Pragma("unroll") for (int n = 0; n < 2; ++n) _Pragma("unroll") for (int k = 0; k < 2; ++k) \
;         acc[ai][bj][m][n] = __builtin_amdgcn_mfma_f32_16x16x32_bf16(Bt[n][k], At[m][k], acc[ai][bj][m][n], 0, 0, 0); __builtin_amdgcn_s_setprio(0); } while (0)
; template <class Epi, class Sched, bool ALIGN_EPI = false, bool SP2 = false>
; __device__ __forceinline__ void gemm_phase(PG8_LAS unsigned char* lds, const Gemm g, const Sched& S, const Epi& E) {
;     ...
;         for (int t = 0; t < nt; t += 2) {
;             if constexpr (Epi::MIDSCALE) { if (t == (nt >> 1)) E.midscale(acc, cur, wr, fr, ui); }
;             const bool last = (t == nt - 2);
;             const char* a1 = cA + (size_t)(t >> 1) * apair + kstep;
;             const char* a2 = last ? nA : cA + (size_t)((t >> 1) + 1) * apair; const char* b2 = last ? nB : cB + (size_t)(t + 2) * kstep;
;             const char* a3 = a2 + kstep; const char* b3 = b2 + kstep;
;             if (last && has_next) S.a_ready(nxt, ui + 1);
;             if constexpr (SP2) {
;             PG8_LDB(B0, 0, 0); PG8_LDB(B1, 0, 1); PG8_SCHED; PG8_LDA(At, 0, 0); PG8_STAGE(PG8_SA(1, 1), a1 + hstepA, voffA);
;             PG8_WAIT_V(8); PG8_WAIT_L(0); PG8_BAR; PG8_MMA(0, 0, At, B0); PG8_MMA(0, 1, At, B1); PG8_BAR; PG8_SCHED;
;             PG8_LDA(At, 0, 1); PG8_STAGE(PG8_SB(0, 0), b2, voffB); PG8_STAGE(PG8_SB(0, 1), b2 + hstep, voffB); PG8_STAGE(PG8_SA(0, 0), a2, voffA);
;             PG8_WAIT_V(8); PG8_WAIT_L(0); PG8_BAR; PG8_MMA(1, 0, At, B0); PG8_MMA(1, 1, At, B1); PG8_BAR; PG8_SCHED;
.LBB0_246:
	s_add_u32 s12, s10, 0xfffc0080
	s_addc_u32 s13, s11, -1
	s_add_i32 s94, 0, 0x10000
	s_cmp_eq_u32 vcc_lo, 12
	s_cselect_b32 s45, s21, s13
	s_cselect_b32 s44, s28, s12
	v_add_u32_e32 v0, s94, v179
	s_cselect_b32 s13, s43, s63
	s_cselect_b32 s12, s46, s47
	s_add_i32 vcc_hi, 0, 0x14000
	ds_read_b128 v[130:133], v0
	ds_read_b128 v[134:137], v0 offset:1024
	ds_read_b128 v[138:141], v0 offset:2048
	ds_read_b128 v[142:145], v0 offset:3072
	v_add_u32_e32 v0, vcc_hi, v179
	ds_read_b128 v[146:149], v0
	ds_read_b128 v[170:173], v0 offset:1024
	ds_read_b128 v[190:193], v0 offset:2048
	ds_read_b128 v[194:197], v0 offset:3072
	v_lshl_add_u64 v[150:151], s[10:11], 0, v[162:163]
	s_add_i32 m0, s17, 0xc000
	ds_read_b128 v[198:201], v186
	ds_read_b128 v[202:205], v186 offset:1024
	ds_read_b128 v[206:209], v186 offset:2048
	ds_read_b128 v[210:213], v186 offset:3072
	ds_read_b128 v[214:217], v186 offset:4096
	ds_read_b128 v[218:221], v186 offset:5120
	ds_read_b128 v[222:225], v186 offset:6144
	ds_read_b128 v[226:229], v186 offset:7168
	global_load_lds_dwordx4 v[150:151], off
	v_lshl_add_u64 v[150:151], s[10:11], 0, v[164:165]
	s_add_i32 m0, s17, 0xe000
	s_nop 0
	global_load_lds_dwordx4 v[150:151], off
	s_waitcnt vmcnt(8)
	s_waitcnt lgkmcnt(0)
	s_barrier
	s_setprio 1
	v_mfma_f32_16x16x32_bf16 v[126:129], v[130:133], v[198:201], v[126:129]
	v_mfma_f32_16x16x32_bf16 v[122:125], v[138:141], v[198:201], v[122:125]
	v_mfma_f32_16x16x32_bf16 v[110:113], v[130:133], v[206:209], v[110:113]
	v_mfma_f32_16x16x32_bf16 v[106:109], v[138:141], v[206:209], v[106:109]
	v_mfma_f32_16x16x32_bf16 v[94:97], v[130:133], v[214:217], v[94:97]
	v_mfma_f32_16x16x32_bf16 v[90:93], v[138:141], v[214:217], v[90:93]
	v_mfma_f32_16x16x32_bf16 v[78:81], v[130:133], v[222:225], v[78:81]
	v_mfma_f32_16x16x32_bf16 v[74:77], v[138:141], v[222:225], v[74:77]
	v_mfma_f32_16x16x32_bf16 v[126:129], v[134:137], v[202:205], v[126:129]
	v_mfma_f32_16x16x32_bf16 v[122:125], v[142:145], v[202:205], v[122:125]
	v_mfma_f32_16x16x32_bf16 v[110:113], v[134:137], v[210:213], v[110:113]
	v_mfma_f32_16x16x32_bf16 v[106:109], v[142:145], v[210:213], v[106:109]
	v_mfma_f32_16x16x32_bf16 v[94:97], v[134:137], v[218:221], v[94:97]
	v_mfma_f32_16x16x32_bf16 v[90:93], v[142:145], v[218:221], v[90:93]
	v_mfma_f32_16x16x32_bf16 v[78:81], v[134:137], v[226:229], v[78:81]
	v_mfma_f32_16x16x32_bf16 v[74:77], v[142:145], v[226:229], v[74:77]
	v_mfma_f32_16x16x32_bf16 v[118:121], v[146:149], v[198:201], v[118:121]
	v_mfma_f32_16x16x32_bf16 v[114:117], v[190:193], v[198:201], v[114:117]
	v_mfma_f32_16x16x32_bf16 v[102:105], v[146:149], v[206:209], v[102:105]
	v_mfma_f32_16x16x32_bf16 v[98:101], v[190:193], v[206:209], v[98:101]
	v_mfma_f32_16x16x32_bf16 v[86:89], v[146:149], v[214:217], v[86:89]
	v_mfma_f32_16x16x32_bf16 v[82:85], v[190:193], v[214:217], v[82:85]
	v_mfma_f32_16x16x32_bf16 v[70:73], v[146:149], v[222:225], v[70:73]
	v_mfma_f32_16x16x32_bf16 v[66:69], v[190:193], v[222:225], v[66:69]
	v_mfma_f32_16x16x32_bf16 v[118:121], v[170:173], v[202:205], v[118:121]
	v_mfma_f32_16x16x32_bf16 v[114:117], v[194:197], v[202:205], v[114:117]
	v_mfma_f32_16x16x32_bf16 v[102:105], v[170:173], v[210:213], v[102:105]
	v_mfma_f32_16x16x32_bf16 v[98:101], v[194:197], v[210:213], v[98:101]
	v_mfma_f32_16x16x32_bf16 v[86:89], v[170:173], v[218:221], v[86:89]
	v_mfma_f32_16x16x32_bf16 v[82:85], v[194:197], v[218:221], v[82:85]
	v_mfma_f32_16x16x32_bf16 v[70:73], v[170:173], v[226:229], v[70:73]
	v_mfma_f32_16x16x32_bf16 v[66:69], v[194:197], v[226:229], v[66:69]
	s_setprio 0
	s_barrier
	s_add_i32 s94, s94, s16
	v_lshl_add_u64 v[150:151], s[12:13], 0, v[156:157]
	s_mov_b32 m0, s94
	ds_read_b128 v[198:201], v186 offset:16384
	ds_read_b128 v[202:205], v186 offset:17408
	ds_read_b128 v[206:209], v186 offset:18432
	ds_read_b128 v[210:213], v186 offset:19456
	ds_read_b128 v[214:217], v186 offset:20480
	ds_read_b128 v[218:221], v186 offset:21504
	ds_read_b128 v[222:225], v186 offset:22528
	ds_read_b128 v[226:229], v186 offset:23552
	global_load_lds_dwordx4 v[150:151], off
	s_add_i32 m0, s94, 0x2000
	s_add_u32 s94, s12, 0x40000
	v_lshl_add_u64 v[166:167], s[12:13], 0, v[160:161]
	s_addc_u32 s95, s13, 0
	s_add_i32 vcc_hi, vcc_hi, s16
	global_load_lds_dwordx4 v[166:167], off
	v_lshl_add_u64 v[230:231], s[94:95], 0, v[156:157]
	s_mov_b32 m0, vcc_hi
	v_lshl_add_u64 v[232:233], s[44:45], 0, v[158:159]
	global_load_lds_dwordx4 v[230:231], off
	v_lshl_add_u64 v[230:231], s[94:95], 0, v[160:161]
	s_add_i32 m0, vcc_hi, 0x2000
	s_nop 0
	global_load_lds_dwordx4 v[230:231], off
	v_lshl_add_u64 v[230:231], s[44:45], 0, v[154:155]
	s_mov_b32 m0, s17
	s_nop 0
	global_load_lds_dwordx4 v[230:231], off
	s_mov_b32 m0, s51
	s_nop 0
	global_load_lds_dwordx4 v[232:233], off
	s_waitcnt vmcnt(8)
	s_waitcnt lgkmcnt(0)
	s_barrier
; #define PG8_STAGE(bufoff, gbase, voff) do { _Pragma("unroll") for (int _i = 0; _i < 2; ++_i) \
;         __builtin_amdgcn_global_load_lds((const unsigned*)((const char*)(gbase) + (voff)[_i]), (PG8_LAS unsigned*)(lds + (bufoff) + ldsw + _i * 8192), 16, 0, 0); } while (0)
; #define PG8_LDA(dst, b, h) do { _Pragma("unroll") for (int m = 0; m < 4; ++m) _Pragma("unroll") for (int k = 0; k < 2; ++k) dst[m][k] = *(const PG8_LAS bf16x8*)(lds + PG8_SA(b, h) + aoff + m * 2048 + k * 1024); } while (0)
; #define PG8_LDB(dst, b, h) do { _Pragma("unroll") for (int n = 0; n < 2; ++n) _Pragma("unroll") for (int k = 0; k < 2; ++k) dst[n][k] = *(const PG8_LAS bf16x8*)(lds + PG8_SB(b, h) + boff + n * 2048 + k * 1024); } while (0)
; #define PG8_MMA(ai, bj, At, Bt) do { __builtin_amdgcn_s_setprio(1); _Pragma("unroll") for (int m = 0; m < 4; ++m) _Pragma("unroll") for (int n = 0; n < 2; ++n) _Pragma("unroll") for (int k = 0; k < 2; ++k) \
;         acc[ai][bj][m][n] = __builtin_amdgcn_mfma_f32_16x16x32_bf16(Bt[n][k], At[m][k], acc[ai][bj][m][n], 0, 0, 0); __builtin_amdgcn_s_setprio(0); } while (0)
; #define PG8_WAIT_V(n) asm volatile("s_waitcnt vmcnt(" #n ")" ::: "memory")
; #define PG8_WAIT_L(n) asm volatile("s_waitcnt lgkmcnt(" #n ")" ::: "memory")
; #define PG8_BAR __builtin_amdgcn_s_barrier()
; #define PG8_SCHED __builtin_amdgcn_sched_barrier(0)
; template <class Epi, class Sched, bool ALIGN_EPI = false, bool SP2 = false>
; __device__ __forceinline__ void gemm_phase(PG8_LAS unsigned char* lds, const Gemm g, const Sched& S, const Epi& E) {
;     ...
;             PG8_WAIT_V(8); PG8_WAIT_L(0); PG8_BAR; PG8_MMA(1, 0, At, B0); PG8_MMA(1, 1, At, B1); PG8_BAR; PG8_SCHED;
;             PG8_LDB(B0, 1, 0); PG8_LDB(B1, 1, 1); PG8_SCHED; PG8_LDA(At, 1, 0); PG8_STAGE(PG8_SA(0, 1), a2 + hstepA, voffA);
;             PG8_WAIT_V(8); PG8_WAIT_L(0); PG8_BAR; PG8_MMA(0, 0, At, B0); PG8_MMA(0, 1, At, B1); PG8_BAR; PG8_SCHED;
	s_setprio 1
	v_mfma_f32_16x16x32_bf16 v[62:65], v[130:133], v[198:201], v[62:65]
	v_mfma_f32_16x16x32_bf16 v[58:61], v[138:141], v[198:201], v[58:61]
	v_mfma_f32_16x16x32_bf16 v[46:49], v[130:133], v[206:209], v[46:49]
	v_mfma_f32_16x16x32_bf16 v[42:45], v[138:141], v[206:209], v[42:45]
	v_mfma_f32_16x16x32_bf16 v[30:33], v[130:133], v[214:217], v[30:33]
	v_mfma_f32_16x16x32_bf16 v[26:29], v[138:141], v[214:217], v[26:29]
	v_mfma_f32_16x16x32_bf16 v[14:17], v[130:133], v[222:225], v[14:17]
	v_mfma_f32_16x16x32_bf16 v[10:13], v[138:141], v[222:225], v[10:13]
	v_mfma_f32_16x16x32_bf16 v[62:65], v[134:137], v[202:205], v[62:65]
	v_mfma_f32_16x16x32_bf16 v[58:61], v[142:145], v[202:205], v[58:61]
	v_mfma_f32_16x16x32_bf16 v[46:49], v[134:137], v[210:213], v[46:49]
	v_mfma_f32_16x16x32_bf16 v[42:45], v[142:145], v[210:213], v[42:45]
	v_mfma_f32_16x16x32_bf16 v[30:33], v[134:137], v[218:221], v[30:33]
	v_mfma_f32_16x16x32_bf16 v[26:29], v[142:145], v[218:221], v[26:29]
	v_mfma_f32_16x16x32_bf16 v[14:17], v[134:137], v[226:229], v[14:17]
	v_mfma_f32_16x16x32_bf16 v[10:13], v[142:145], v[226:229], v[10:13]
	v_mfma_f32_16x16x32_bf16 v[54:57], v[146:149], v[198:201], v[54:57]
	v_mfma_f32_16x16x32_bf16 v[50:53], v[190:193], v[198:201], v[50:53]
	v_mfma_f32_16x16x32_bf16 v[38:41], v[146:149], v[206:209], v[38:41]
	v_mfma_f32_16x16x32_bf16 v[34:37], v[190:193], v[206:209], v[34:37]
	v_mfma_f32_16x16x32_bf16 v[22:25], v[146:149], v[214:217], v[22:25]
	v_mfma_f32_16x16x32_bf16 v[18:21], v[190:193], v[214:217], v[18:21]
	v_mfma_f32_16x16x32_bf16 v[6:9], v[146:149], v[222:225], v[6:9]
	v_mfma_f32_16x16x32_bf16 v[2:5], v[190:193], v[222:225], v[2:5]
	v_mfma_f32_16x16x32_bf16 v[54:57], v[170:173], v[202:205], v[54:57]
	v_mfma_f32_16x16x32_bf16 v[50:53], v[194:197], v[202:205], v[50:53]
	v_mfma_f32_16x16x32_bf16 v[38:41], v[170:173], v[210:213], v[38:41]
	v_mfma_f32_16x16x32_bf16 v[34:37], v[194:197], v[210:213], v[34:37]
	v_mfma_f32_16x16x32_bf16 v[22:25], v[170:173], v[218:221], v[22:25]
	v_mfma_f32_16x16x32_bf16 v[18:21], v[194:197], v[218:221], v[18:21]
	v_mfma_f32_16x16x32_bf16 v[6:9], v[170:173], v[226:229], v[6:9]
	v_mfma_f32_16x16x32_bf16 v[2:5], v[194:197], v[226:229], v[2:5]
	s_setprio 0
	s_barrier
	s_add_i32 s94, 0, 0x18000
	v_add_u32_e32 v0, s94, v179
	s_add_i32 s95, 0, 0x1c000
	ds_read_b128 v[130:133], v0
	ds_read_b128 v[134:137], v0 offset:1024
	ds_read_b128 v[138:141], v0 offset:2048
	ds_read_b128 v[142:145], v0 offset:3072
	v_add_u32_e32 v0, s95, v179
	ds_read_b128 v[146:149], v0
	ds_read_b128 v[170:173], v0 offset:1024
	ds_read_b128 v[190:193], v0 offset:2048
	ds_read_b128 v[194:197], v0 offset:3072
	s_add_u32 s44, s44, 0x40000
	s_addc_u32 s45, s45, 0
	s_mov_b32 m0, s35
	v_lshl_add_u64 v[234:235], s[44:45], 0, v[154:155]
	ds_read_b128 v[198:201], v186 offset:32768
	ds_read_b128 v[202:205], v186 offset:33792
	ds_read_b128 v[206:209], v186 offset:34816
	ds_read_b128 v[210:213], v186 offset:35840
	ds_read_b128 v[214:217], v186 offset:36864
	ds_read_b128 v[218:221], v186 offset:37888
	ds_read_b128 v[222:225], v186 offset:38912
	ds_read_b128 v[226:229], v186 offset:39936
	global_load_lds_dwordx4 v[234:235], off
	v_lshl_add_u64 v[234:235], s[44:45], 0, v[158:159]
	s_mov_b32 m0, s30
	s_nop 0
	global_load_lds_dwordx4 v[234:235], off
	s_waitcnt vmcnt(8)
	s_waitcnt lgkmcnt(0)
	s_barrier
	s_setprio 1
	v_mfma_f32_16x16x32_bf16 v[126:129], v[130:133], v[198:201], v[126:129]
	v_mfma_f32_16x16x32_bf16 v[122:125], v[138:141], v[198:201], v[122:125]
	v_mfma_f32_16x16x32_bf16 v[110:113], v[130:133], v[206:209], v[110:113]
	v_mfma_f32_16x16x32_bf16 v[106:109], v[138:141], v[206:209], v[106:109]
	v_mfma_f32_16x16x32_bf16 v[94:97], v[130:133], v[214:217], v[94:97]
	v_mfma_f32_16x16x32_bf16 v[90:93], v[138:141], v[214:217], v[90:93]
	v_mfma_f32_16x16x32_bf16 v[78:81], v[130:133], v[222:225], v[78:81]
	v_mfma_f32_16x16x32_bf16 v[74:77], v[138:141], v[222:225], v[74:77]
	v_mfma_f32_16x16x32_bf16 v[126:129], v[134:137], v[202:205], v[126:129]
	v_mfma_f32_16x16x32_bf16 v[122:125], v[142:145], v[202:205], v[122:125]
	v_mfma_f32_16x16x32_bf16 v[110:113], v[134:137], v[210:213], v[110:113]
	v_mfma_f32_16x16x32_bf16 v[106:109], v[142:145], v[210:213], v[106:109]
	v_mfma_f32_16x16x32_bf16 v[94:97], v[134:137], v[218:221], v[94:97]
	v_mfma_f32_16x16x32_bf16 v[90:93], v[142:145], v[218:221], v[90:93]
	v_mfma_f32_16x16x32_bf16 v[78:81], v[134:137], v[226:229], v[78:81]
	v_mfma_f32_16x16x32_bf16 v[74:77], v[142:145], v[226:229], v[74:77]
	v_mfma_f32_16x16x32_bf16 v[118:121], v[146:149], v[198:201], v[118:121]
	v_mfma_f32_16x16x32_bf16 v[114:117], v[190:193], v[198:201], v[114:117]
	v_mfma_f32_16x16x32_bf16 v[102:105], v[146:149], v[206:209], v[102:105]
	v_mfma_f32_16x16x32_bf16 v[98:101], v[190:193], v[206:209], v[98:101]
	v_mfma_f32_16x16x32_bf16 v[86:89], v[146:149], v[214:217], v[86:89]
	v_mfma_f32_16x16x32_bf16 v[82:85], v[190:193], v[214:217], v[82:85]
	v_mfma_f32_16x16x32_bf16 v[70:73], v[146:149], v[222:225], v[70:73]
	v_mfma_f32_16x16x32_bf16 v[66:69], v[190:193], v[222:225], v[66:69]
	v_mfma_f32_16x16x32_bf16 v[118:121], v[170:173], v[202:205], v[118:121]
	v_mfma_f32_16x16x32_bf16 v[114:117], v[194:197], v[202:205], v[114:117]
	v_mfma_f32_16x16x32_bf16 v[102:105], v[170:173], v[210:213], v[102:105]
	v_mfma_f32_16x16x32_bf16 v[98:101], v[194:197], v[210:213], v[98:101]
	v_mfma_f32_16x16x32_bf16 v[86:89], v[170:173], v[218:221], v[86:89]
	v_mfma_f32_16x16x32_bf16 v[82:85], v[194:197], v[218:221], v[82:85]
	v_mfma_f32_16x16x32_bf16 v[70:73], v[170:173], v[226:229], v[70:73]
	v_mfma_f32_16x16x32_bf16 v[66:69], v[194:197], v[226:229], v[66:69]
	s_setprio 0
	s_barrier
; #define PG8_STAGE(bufoff, gbase, voff) do { _Pragma("unroll") for (int _i = 0; _i < 2; ++_i) \
;         __builtin_amdgcn_global_load_lds((const unsigned*)((const char*)(gbase) + (voff)[_i]), (PG8_LAS unsigned*)(lds + (bufoff) + ldsw + _i * 8192), 16, 0, 0); } while (0)
; #define PG8_LDA(dst, b, h) do { _Pragma("unroll") for (int m = 0; m < 4; ++m) _Pragma("unroll") for (int k = 0; k < 2; ++k) dst[m][k] = *(const PG8_LAS bf16x8*)(lds + PG8_SA(b, h) + aoff + m * 2048 + k * 1024); } while (0)
; #define PG8_MMA(ai, bj, At, Bt) do { __builtin_amdgcn_s_setprio(1); _Pragma("unroll") for (int m = 0; m < 4; ++m) _Pragma("unroll") for (int n = 0; n < 2; ++n) _Pragma("unroll") for (int k = 0; k < 2; ++k) \
;         acc[ai][bj][m][n] = __builtin_amdgcn_mfma_f32_16x16x32_bf16(Bt[n][k], At[m][k], acc[ai][bj][m][n], 0, 0, 0); __builtin_amdgcn_s_setprio(0); } while (0)
; #define PG8_WAIT_V(n) asm volatile("s_waitcnt vmcnt(" #n ")" ::: "memory")
; #define PG8_WAIT_L(n) asm volatile("s_waitcnt lgkmcnt(" #n ")" ::: "memory")
; #define PG8_BAR __builtin_amdgcn_s_barrier()
; #define PG8_SCHED __builtin_amdgcn_sched_barrier(0)
; template <class Epi, class Sched, bool ALIGN_EPI = false, bool SP2 = false>
; __device__ __forceinline__ void gemm_phase(PG8_LAS unsigned char* lds, const Gemm g, const Sched& S, const Epi& E) {
;     ...
;         for (int t = 0; t < nt; t += 2) {
;     ...
;             PG8_LDA(At, 1, 1); PG8_STAGE(PG8_SB(1, 0), b3, voffB); PG8_STAGE(PG8_SB(1, 1), b3 + hstep, voffB); PG8_STAGE(PG8_SA(1, 0), a3, voffA);
;             PG8_WAIT_V(8); PG8_WAIT_L(0); PG8_BAR; PG8_MMA(1, 0, At, B0); PG8_MMA(1, 1, At, B1); PG8_BAR; PG8_SCHED;
;     ...
;         if (!has_next) break;
	s_add_i32 s44, s94, s16
	v_lshl_add_u64 v[150:151], v[150:151], 0, s[48:49]
	s_mov_b32 m0, s44
	ds_read_b128 v[198:201], v186 offset:49152
	ds_read_b128 v[202:205], v186 offset:50176
	ds_read_b128 v[206:209], v186 offset:51200
	ds_read_b128 v[210:213], v186 offset:52224
	ds_read_b128 v[214:217], v186 offset:53248
	ds_read_b128 v[218:221], v186 offset:54272
	ds_read_b128 v[222:225], v186 offset:55296
	ds_read_b128 v[226:229], v186 offset:56320
	global_load_lds_dwordx4 v[150:151], off
	s_add_i32 m0, s44, 0x2000
	s_add_u32 s12, s12, 0x40080
	v_lshl_add_u64 v[150:151], v[166:167], 0, s[48:49]
	s_addc_u32 s13, s13, 0
	s_add_i32 s44, s95, s16
	global_load_lds_dwordx4 v[150:151], off
	v_lshl_add_u64 v[150:151], s[12:13], 0, v[156:157]
	s_mov_b32 m0, s44
	s_nop 0
	global_load_lds_dwordx4 v[150:151], off
	v_lshl_add_u64 v[150:151], s[12:13], 0, v[160:161]
	s_add_i32 m0, s44, 0x2000
	s_nop 0
	global_load_lds_dwordx4 v[150:151], off
	v_lshl_add_u64 v[150:151], v[230:231], 0, s[48:49]
	s_mov_b32 m0, s59
	s_nop 0
	global_load_lds_dwordx4 v[150:151], off
	v_lshl_add_u64 v[150:151], v[232:233], 0, s[48:49]
	s_mov_b32 m0, s86
	s_nop 0
	global_load_lds_dwordx4 v[150:151], off
	s_waitcnt vmcnt(8)
	s_waitcnt lgkmcnt(0)
	s_barrier
	s_setprio 1
	v_mfma_f32_16x16x32_bf16 v[62:65], v[130:133], v[198:201], v[62:65]
	v_mfma_f32_16x16x32_bf16 v[58:61], v[138:141], v[198:201], v[58:61]
	v_mfma_f32_16x16x32_bf16 v[46:49], v[130:133], v[206:209], v[46:49]
	v_mfma_f32_16x16x32_bf16 v[42:45], v[138:141], v[206:209], v[42:45]
	v_mfma_f32_16x16x32_bf16 v[30:33], v[130:133], v[214:217], v[30:33]
	v_mfma_f32_16x16x32_bf16 v[26:29], v[138:141], v[214:217], v[26:29]
	v_mfma_f32_16x16x32_bf16 v[14:17], v[130:133], v[222:225], v[14:17]
	v_mfma_f32_16x16x32_bf16 v[10:13], v[138:141], v[222:225], v[10:13]
	v_mfma_f32_16x16x32_bf16 v[62:65], v[134:137], v[202:205], v[62:65]
	v_mfma_f32_16x16x32_bf16 v[58:61], v[142:145], v[202:205], v[58:61]
	v_mfma_f32_16x16x32_bf16 v[46:49], v[134:137], v[210:213], v[46:49]
	v_mfma_f32_16x16x32_bf16 v[42:45], v[142:145], v[210:213], v[42:45]
	v_mfma_f32_16x16x32_bf16 v[30:33], v[134:137], v[218:221], v[30:33]
	v_mfma_f32_16x16x32_bf16 v[26:29], v[142:145], v[218:221], v[26:29]
	v_mfma_f32_16x16x32_bf16 v[14:17], v[134:137], v[226:229], v[14:17]
	v_mfma_f32_16x16x32_bf16 v[10:13], v[142:145], v[226:229], v[10:13]
	v_mfma_f32_16x16x32_bf16 v[54:57], v[146:149], v[198:201], v[54:57]
	v_mfma_f32_16x16x32_bf16 v[50:53], v[190:193], v[198:201], v[50:53]
	v_mfma_f32_16x16x32_bf16 v[38:41], v[146:149], v[206:209], v[38:41]
	v_mfma_f32_16x16x32_bf16 v[34:37], v[190:193], v[206:209], v[34:37]
	v_mfma_f32_16x16x32_bf16 v[22:25], v[146:149], v[214:217], v[22:25]
	v_mfma_f32_16x16x32_bf16 v[18:21], v[190:193], v[214:217], v[18:21]
	v_mfma_f32_16x16x32_bf16 v[6:9], v[146:149], v[222:225], v[6:9]
	v_mfma_f32_16x16x32_bf16 v[2:5], v[190:193], v[222:225], v[2:5]
	v_mfma_f32_16x16x32_bf16 v[54:57], v[170:173], v[202:205], v[54:57]
	v_mfma_f32_16x16x32_bf16 v[50:53], v[194:197], v[202:205], v[50:53]
	v_mfma_f32_16x16x32_bf16 v[38:41], v[170:173], v[210:213], v[38:41]
	v_mfma_f32_16x16x32_bf16 v[34:37], v[194:197], v[210:213], v[34:37]
	v_mfma_f32_16x16x32_bf16 v[22:25], v[170:173], v[218:221], v[22:25]
	v_mfma_f32_16x16x32_bf16 v[18:21], v[194:197], v[218:221], v[18:21]
	v_mfma_f32_16x16x32_bf16 v[6:9], v[170:173], v[226:229], v[6:9]
	v_mfma_f32_16x16x32_bf16 v[2:5], v[194:197], v[226:229], v[2:5]
	s_setprio 0
	s_barrier
	s_add_i32 vcc_lo, vcc_lo, 2
	s_add_u32 s10, s10, 0x100
	s_addc_u32 s11, s11, 0
	s_add_u32 s47, s47, 0x100
	s_addc_u32 s63, s63, 0
	s_cmp_gt_u32 vcc_lo, 13
	s_cbranch_scc0 .LBB0_246
	s_and_b64 vcc, exec, s[88:89]
	s_cbranch_vccz .LBB0_249
	s_barrier

; #define PG8_STAGE(bufoff, gbase, voff) do { _Pragma("unroll") for (int _i = 0; _i < 2; ++_i) \
;         __builtin_amdgcn_global_load_lds((const unsigned*)((const char*)(gbase) + (voff)[_i]), (PG8_LAS unsigned*)(lds + (bufoff) + ldsw + _i * 8192), 16, 0, 0); } while (0)
; #define PG8_LDA(dst, b, h) do { _Pragma("unroll") for (int m = 0; m < 4; ++m) _Pragma("unroll") for (int k = 0; k < 2; ++k) dst[m][k] = *(const PG8_LAS bf16x8*)(lds + PG8_SA(b, h) + aoff + m * 2048 + k * 1024); } while (0)
; #define PG8_LDB(dst, b, h) do { _Pragma("unroll") for (int n = 0; n < 2; ++n) _Pragma("unroll") for (int k = 0; k < 2; ++k) dst[n][k] = *(const PG8_LAS bf16x8*)(lds + PG8_SB(b, h) + boff + n * 2048 + k * 1024); } while (0)
; #define PG8_MMA(ai, bj, At, Bt) do { __builtin_amdgcn_s_setprio(1); _Pragma("unroll") for (int m = 0; m < 4; ++m) _Pragma("unroll") for (int n = 0; n < 2; ++n) _Pragma("unroll") for (int k = 0; k < 2; ++k) \
;         acc[ai][bj][m][n] = __builtin_amdgcn_mfma_f32_16x16x32_bf16(Bt[n][k], At[m][k], acc[ai][bj][m][n], 0, 0, 0); __builtin_amdgcn_s_setprio(0); } while (0)
; template <class Epi, class Sched, bool ALIGN_EPI = false, bool SP2 = false>
; __device__ __forceinline__ void gemm_phase(PG8_LAS unsigned char* lds, const Gemm g, const Sched& S, const Epi& E) {
;     ...
;         for (int t = 0; t < nt; t += 2) {
;             if constexpr (Epi::MIDSCALE) { if (t == (nt >> 1)) E.midscale(acc, cur, wr, fr, ui); }
;             const bool last = (t == nt - 2);
;             const char* a1 = cA + (size_t)(t >> 1) * apair + kstep;
;             const char* a2 = last ? nA : cA + (size_t)((t >> 1) + 1) * apair; const char* b2 = last ? nB : cB + (size_t)(t + 2) * kstep;
;             const char* a3 = a2 + kstep; const char* b3 = b2 + kstep;
;             if (last && has_next) S.a_ready(nxt, ui + 1);
;             if constexpr (SP2) {
;             PG8_LDB(B0, 0, 0); PG8_LDB(B1, 0, 1); PG8_SCHED; PG8_LDA(At, 0, 0); PG8_STAGE(PG8_SA(1, 1), a1 + hstepA, voffA);
;             PG8_WAIT_V(8); PG8_WAIT_L(0); PG8_BAR; PG8_MMA(0, 0, At, B0); PG8_MMA(0, 1, At, B1); PG8_BAR; PG8_SCHED;
;             PG8_LDA(At, 0, 1); PG8_STAGE(PG8_SB(0, 0), b2, voffB); PG8_STAGE(PG8_SB(0, 1), b2 + hstep, voffB); PG8_STAGE(PG8_SA(0, 0), a2, voffA);
;             PG8_WAIT_V(8); PG8_WAIT_L(0); PG8_BAR; PG8_MMA(1, 0, At, B0); PG8_MMA(1, 1, At, B1); PG8_BAR; PG8_SCHED;
.LBB0_386:
	s_add_u32 s66, s42, s64
	s_addc_u32 s67, s43, s65
	s_add_u32 s66, s66, 0x1080000
	s_addc_u32 s67, s67, 0
	s_and_b64 s[44:45], s[44:45], exec
	s_cselect_b32 s45, s51, s67
	s_cselect_b32 s44, s78, s66
	s_cselect_b32 s67, s79, s84
	s_cselect_b32 s66, s80, s83
	s_add_i32 s86, 0, 0x10000
	v_add_u32_e32 v0, s86, v154
	s_add_i32 s88, 0, 0x14000
	ds_read_b128 v[158:161], v0
	ds_read_b128 v[162:165], v0 offset:1024
	ds_read_b128 v[178:181], v0 offset:2048
	ds_read_b128 v[182:185], v0 offset:3072
	v_add_u32_e32 v0, s88, v154
	ds_read_b128 v[186:189], v0
	ds_read_b128 v[190:193], v0 offset:1024
	ds_read_b128 v[194:197], v0 offset:2048
	ds_read_b128 v[198:201], v0 offset:3072
	v_lshl_add_u64 v[2:3], v[144:145], 0, s[64:65]
	s_add_i32 m0, s35, 0xc000
	ds_read_b128 v[202:205], v156
	ds_read_b128 v[206:209], v156 offset:1024
	ds_read_b128 v[210:213], v156 offset:2048
	ds_read_b128 v[214:217], v156 offset:3072
	ds_read_b128 v[218:221], v156 offset:4096
	ds_read_b128 v[222:225], v156 offset:5120
	ds_read_b128 v[226:229], v156 offset:6144
	ds_read_b128 v[230:233], v156 offset:7168
	global_load_lds_dwordx4 v[2:3], off
	v_lshl_add_u64 v[2:3], v[146:147], 0, s[64:65]
	s_add_i32 m0, s35, 0xe000
	s_nop 0
	global_load_lds_dwordx4 v[2:3], off
	s_waitcnt vmcnt(8)
	s_waitcnt lgkmcnt(0)
	s_barrier
	s_setprio 1
	v_mfma_f32_16x16x32_bf16 v[128:131], v[158:161], v[202:205], v[128:131]
	v_mfma_f32_16x16x32_bf16 v[124:127], v[178:181], v[202:205], v[124:127]
	v_mfma_f32_16x16x32_bf16 v[112:115], v[158:161], v[210:213], v[112:115]
	v_mfma_f32_16x16x32_bf16 v[108:111], v[178:181], v[210:213], v[108:111]
	v_mfma_f32_16x16x32_bf16 v[96:99], v[158:161], v[218:221], v[96:99]
	v_mfma_f32_16x16x32_bf16 v[92:95], v[178:181], v[218:221], v[92:95]
	v_mfma_f32_16x16x32_bf16 v[80:83], v[158:161], v[226:229], v[80:83]
	v_mfma_f32_16x16x32_bf16 v[76:79], v[178:181], v[226:229], v[76:79]
	v_mfma_f32_16x16x32_bf16 v[128:131], v[162:165], v[206:209], v[128:131]
	v_mfma_f32_16x16x32_bf16 v[124:127], v[182:185], v[206:209], v[124:127]
	v_mfma_f32_16x16x32_bf16 v[112:115], v[162:165], v[214:217], v[112:115]
	v_mfma_f32_16x16x32_bf16 v[108:111], v[182:185], v[214:217], v[108:111]
	v_mfma_f32_16x16x32_bf16 v[96:99], v[162:165], v[222:225], v[96:99]
	v_mfma_f32_16x16x32_bf16 v[92:95], v[182:185], v[222:225], v[92:95]
	v_mfma_f32_16x16x32_bf16 v[80:83], v[162:165], v[230:233], v[80:83]
	v_mfma_f32_16x16x32_bf16 v[76:79], v[182:185], v[230:233], v[76:79]
	v_mfma_f32_16x16x32_bf16 v[120:123], v[186:189], v[202:205], v[120:123]
	v_mfma_f32_16x16x32_bf16 v[116:119], v[194:197], v[202:205], v[116:119]
	v_mfma_f32_16x16x32_bf16 v[104:107], v[186:189], v[210:213], v[104:107]
	v_mfma_f32_16x16x32_bf16 v[100:103], v[194:197], v[210:213], v[100:103]
	v_mfma_f32_16x16x32_bf16 v[88:91], v[186:189], v[218:221], v[88:91]
	v_mfma_f32_16x16x32_bf16 v[84:87], v[194:197], v[218:221], v[84:87]
	v_mfma_f32_16x16x32_bf16 v[72:75], v[186:189], v[226:229], v[72:75]
	v_mfma_f32_16x16x32_bf16 v[68:71], v[194:197], v[226:229], v[68:71]
	v_mfma_f32_16x16x32_bf16 v[120:123], v[190:193], v[206:209], v[120:123]
	v_mfma_f32_16x16x32_bf16 v[116:119], v[198:201], v[206:209], v[116:119]
	v_mfma_f32_16x16x32_bf16 v[104:107], v[190:193], v[214:217], v[104:107]
	v_mfma_f32_16x16x32_bf16 v[100:103], v[198:201], v[214:217], v[100:103]
	v_mfma_f32_16x16x32_bf16 v[88:91], v[190:193], v[222:225], v[88:91]
	v_mfma_f32_16x16x32_bf16 v[84:87], v[198:201], v[222:225], v[84:87]
	v_mfma_f32_16x16x32_bf16 v[72:75], v[190:193], v[230:233], v[72:75]
	v_mfma_f32_16x16x32_bf16 v[68:71], v[198:201], v[230:233], v[68:71]
	s_setprio 0
	s_barrier
	s_add_i32 s86, s86, s30
	v_lshl_add_u64 v[150:151], s[66:67], 0, v[134:135]
	s_mov_b32 m0, s86
	ds_read_b128 v[202:205], v156 offset:16384
	ds_read_b128 v[206:209], v156 offset:17408
	ds_read_b128 v[210:213], v156 offset:18432
	ds_read_b128 v[214:217], v156 offset:19456
	ds_read_b128 v[218:221], v156 offset:20480
	ds_read_b128 v[222:225], v156 offset:21504
	ds_read_b128 v[226:229], v156 offset:22528
	ds_read_b128 v[230:233], v156 offset:23552
	global_load_lds_dwordx4 v[150:151], off
	s_add_i32 m0, s86, 0x2000
	s_add_u32 s86, s66, 0x80000
	v_lshl_add_u64 v[166:167], s[66:67], 0, v[138:139]
	s_addc_u32 s87, s67, 0
	s_add_i32 s88, s88, s30
	global_load_lds_dwordx4 v[166:167], off
	v_lshl_add_u64 v[2:3], s[86:87], 0, v[134:135]
	s_mov_b32 m0, s88
	v_lshl_add_u64 v[170:171], s[44:45], 0, v[132:133]
	global_load_lds_dwordx4 v[2:3], off
	v_lshl_add_u64 v[2:3], s[86:87], 0, v[138:139]
	s_add_i32 m0, s88, 0x2000
	v_lshl_add_u64 v[172:173], s[44:45], 0, v[136:137]
	global_load_lds_dwordx4 v[2:3], off
	s_mov_b32 m0, s35
	s_nop 0
	global_load_lds_dwordx4 v[170:171], off
	s_mov_b32 m0, s46
	s_nop 0
	global_load_lds_dwordx4 v[172:173], off
	s_waitcnt vmcnt(8)
	s_waitcnt lgkmcnt(0)
	s_barrier
; #define PG8_STAGE(bufoff, gbase, voff) do { _Pragma("unroll") for (int _i = 0; _i < 2; ++_i) \
;         __builtin_amdgcn_global_load_lds((const unsigned*)((const char*)(gbase) + (voff)[_i]), (PG8_LAS unsigned*)(lds + (bufoff) + ldsw + _i * 8192), 16, 0, 0); } while (0)
; #define PG8_LDA(dst, b, h) do { _Pragma("unroll") for (int m = 0; m < 4; ++m) _Pragma("unroll") for (int k = 0; k < 2; ++k) dst[m][k] = *(const PG8_LAS bf16x8*)(lds + PG8_SA(b, h) + aoff + m * 2048 + k * 1024); } while (0)
; #define PG8_LDB(dst, b, h) do { _Pragma("unroll") for (int n = 0; n < 2; ++n) _Pragma("unroll") for (int k = 0; k < 2; ++k) dst[n][k] = *(const PG8_LAS bf16x8*)(lds + PG8_SB(b, h) + boff + n * 2048 + k * 1024); } while (0)
; #define PG8_MMA(ai, bj, At, Bt) do { __builtin_amdgcn_s_setprio(1); _Pragma("unroll") for (int m = 0; m < 4; ++m) _Pragma("unroll") for (int n = 0; n < 2; ++n) _Pragma("unroll") for (int k = 0; k < 2; ++k) \
;         acc[ai][bj][m][n] = __builtin_amdgcn_mfma_f32_16x16x32_bf16(Bt[n][k], At[m][k], acc[ai][bj][m][n], 0, 0, 0); __builtin_amdgcn_s_setprio(0); } while (0)
; #define PG8_WAIT_V(n) asm volatile("s_waitcnt vmcnt(" #n ")" ::: "memory")
; #define PG8_WAIT_L(n) asm volatile("s_waitcnt lgkmcnt(" #n ")" ::: "memory")
; #define PG8_BAR __builtin_amdgcn_s_barrier()
; #define PG8_SCHED __builtin_amdgcn_sched_barrier(0)
; template <class Epi, class Sched, bool ALIGN_EPI = false, bool SP2 = false>
; __device__ __forceinline__ void gemm_phase(PG8_LAS unsigned char* lds, const Gemm g, const Sched& S, const Epi& E) {
;     ...
;             PG8_WAIT_V(8); PG8_WAIT_L(0); PG8_BAR; PG8_MMA(1, 0, At, B0); PG8_MMA(1, 1, At, B1); PG8_BAR; PG8_SCHED;
;             PG8_LDB(B0, 1, 0); PG8_LDB(B1, 1, 1); PG8_SCHED; PG8_LDA(At, 1, 0); PG8_STAGE(PG8_SA(0, 1), a2 + hstepA, voffA);
;             PG8_WAIT_V(8); PG8_WAIT_L(0); PG8_BAR; PG8_MMA(0, 0, At, B0); PG8_MMA(0, 1, At, B1); PG8_BAR; PG8_SCHED;
	s_setprio 1
	v_mfma_f32_16x16x32_bf16 v[64:67], v[158:161], v[202:205], v[64:67]
	v_mfma_f32_16x16x32_bf16 v[60:63], v[178:181], v[202:205], v[60:63]
	v_mfma_f32_16x16x32_bf16 v[48:51], v[158:161], v[210:213], v[48:51]
	v_mfma_f32_16x16x32_bf16 v[44:47], v[178:181], v[210:213], v[44:47]
	v_mfma_f32_16x16x32_bf16 v[32:35], v[158:161], v[218:221], v[32:35]
	v_mfma_f32_16x16x32_bf16 v[28:31], v[178:181], v[218:221], v[28:31]
	v_mfma_f32_16x16x32_bf16 v[16:19], v[158:161], v[226:229], v[16:19]
	v_mfma_f32_16x16x32_bf16 v[12:15], v[178:181], v[226:229], v[12:15]
	v_mfma_f32_16x16x32_bf16 v[64:67], v[162:165], v[206:209], v[64:67]
	v_mfma_f32_16x16x32_bf16 v[60:63], v[182:185], v[206:209], v[60:63]
	v_mfma_f32_16x16x32_bf16 v[48:51], v[162:165], v[214:217], v[48:51]
	v_mfma_f32_16x16x32_bf16 v[44:47], v[182:185], v[214:217], v[44:47]
	v_mfma_f32_16x16x32_bf16 v[32:35], v[162:165], v[222:225], v[32:35]
	v_mfma_f32_16x16x32_bf16 v[28:31], v[182:185], v[222:225], v[28:31]
	v_mfma_f32_16x16x32_bf16 v[16:19], v[162:165], v[230:233], v[16:19]
	v_mfma_f32_16x16x32_bf16 v[12:15], v[182:185], v[230:233], v[12:15]
	v_mfma_f32_16x16x32_bf16 v[56:59], v[186:189], v[202:205], v[56:59]
	v_mfma_f32_16x16x32_bf16 v[52:55], v[194:197], v[202:205], v[52:55]
	v_mfma_f32_16x16x32_bf16 v[40:43], v[186:189], v[210:213], v[40:43]
	v_mfma_f32_16x16x32_bf16 v[36:39], v[194:197], v[210:213], v[36:39]
	v_mfma_f32_16x16x32_bf16 v[24:27], v[186:189], v[218:221], v[24:27]
	v_mfma_f32_16x16x32_bf16 v[20:23], v[194:197], v[218:221], v[20:23]
	v_mfma_f32_16x16x32_bf16 v[8:11], v[186:189], v[226:229], v[8:11]
	v_mfma_f32_16x16x32_bf16 v[2:5], v[194:197], v[226:229], v[4:7]
	v_mfma_f32_16x16x32_bf16 v[56:59], v[190:193], v[206:209], v[56:59]
	v_mfma_f32_16x16x32_bf16 v[52:55], v[198:201], v[206:209], v[52:55]
	v_mfma_f32_16x16x32_bf16 v[40:43], v[190:193], v[214:217], v[40:43]
	v_mfma_f32_16x16x32_bf16 v[36:39], v[198:201], v[214:217], v[36:39]
	v_mfma_f32_16x16x32_bf16 v[24:27], v[190:193], v[222:225], v[24:27]
	v_mfma_f32_16x16x32_bf16 v[20:23], v[198:201], v[222:225], v[20:23]
	v_mfma_f32_16x16x32_bf16 v[8:11], v[190:193], v[230:233], v[8:11]
	v_mfma_f32_16x16x32_bf16 v[2:5], v[198:201], v[230:233], v[2:5]
	s_setprio 0
	s_barrier
	s_add_i32 s86, 0, 0x18000
	v_add_u32_e32 v0, s86, v154
	s_add_i32 s87, 0, 0x1c000
	ds_read_b128 v[158:161], v0
	ds_read_b128 v[162:165], v0 offset:1024
	ds_read_b128 v[178:181], v0 offset:2048
	ds_read_b128 v[182:185], v0 offset:3072
	v_add_u32_e32 v0, s87, v154
	ds_read_b128 v[186:189], v0
	ds_read_b128 v[190:193], v0 offset:1024
	ds_read_b128 v[194:197], v0 offset:2048
	ds_read_b128 v[198:201], v0 offset:3072
	s_add_u32 s44, s44, 0x8000
	s_addc_u32 s45, s45, 0
	s_mov_b32 m0, s47
	v_lshl_add_u64 v[6:7], s[44:45], 0, v[132:133]
	ds_read_b128 v[202:205], v156 offset:32768
	ds_read_b128 v[206:209], v156 offset:33792
	ds_read_b128 v[210:213], v156 offset:34816
	ds_read_b128 v[214:217], v156 offset:35840
	ds_read_b128 v[218:221], v156 offset:36864
	ds_read_b128 v[222:225], v156 offset:37888
	ds_read_b128 v[226:229], v156 offset:38912
	ds_read_b128 v[230:233], v156 offset:39936
	global_load_lds_dwordx4 v[6:7], off
	v_lshl_add_u64 v[6:7], s[44:45], 0, v[136:137]
	s_mov_b32 m0, s68
	s_nop 0
	global_load_lds_dwordx4 v[6:7], off
	s_waitcnt vmcnt(8)
	s_waitcnt lgkmcnt(0)
	s_barrier
	s_setprio 1
	v_mfma_f32_16x16x32_bf16 v[128:131], v[158:161], v[202:205], v[128:131]
	v_mfma_f32_16x16x32_bf16 v[124:127], v[178:181], v[202:205], v[124:127]
	v_mfma_f32_16x16x32_bf16 v[112:115], v[158:161], v[210:213], v[112:115]
	v_mfma_f32_16x16x32_bf16 v[108:111], v[178:181], v[210:213], v[108:111]
	v_mfma_f32_16x16x32_bf16 v[96:99], v[158:161], v[218:221], v[96:99]
	v_mfma_f32_16x16x32_bf16 v[92:95], v[178:181], v[218:221], v[92:95]
	v_mfma_f32_16x16x32_bf16 v[80:83], v[158:161], v[226:229], v[80:83]
	v_mfma_f32_16x16x32_bf16 v[76:79], v[178:181], v[226:229], v[76:79]
	v_mfma_f32_16x16x32_bf16 v[128:131], v[162:165], v[206:209], v[128:131]
	v_mfma_f32_16x16x32_bf16 v[124:127], v[182:185], v[206:209], v[124:127]
	v_mfma_f32_16x16x32_bf16 v[112:115], v[162:165], v[214:217], v[112:115]
	v_mfma_f32_16x16x32_bf16 v[108:111], v[182:185], v[214:217], v[108:111]
	v_mfma_f32_16x16x32_bf16 v[96:99], v[162:165], v[222:225], v[96:99]
	v_mfma_f32_16x16x32_bf16 v[92:95], v[182:185], v[222:225], v[92:95]
	v_mfma_f32_16x16x32_bf16 v[80:83], v[162:165], v[230:233], v[80:83]
	v_mfma_f32_16x16x32_bf16 v[76:79], v[182:185], v[230:233], v[76:79]
	v_mfma_f32_16x16x32_bf16 v[120:123], v[186:189], v[202:205], v[120:123]
	v_mfma_f32_16x16x32_bf16 v[116:119], v[194:197], v[202:205], v[116:119]
	v_mfma_f32_16x16x32_bf16 v[104:107], v[186:189], v[210:213], v[104:107]
	v_mfma_f32_16x16x32_bf16 v[100:103], v[194:197], v[210:213], v[100:103]
	v_mfma_f32_16x16x32_bf16 v[88:91], v[186:189], v[218:221], v[88:91]
	v_mfma_f32_16x16x32_bf16 v[84:87], v[194:197], v[218:221], v[84:87]
	v_mfma_f32_16x16x32_bf16 v[72:75], v[186:189], v[226:229], v[72:75]
	v_mfma_f32_16x16x32_bf16 v[68:71], v[194:197], v[226:229], v[68:71]
	v_mfma_f32_16x16x32_bf16 v[120:123], v[190:193], v[206:209], v[120:123]
	v_mfma_f32_16x16x32_bf16 v[116:119], v[198:201], v[206:209], v[116:119]
	v_mfma_f32_16x16x32_bf16 v[104:107], v[190:193], v[214:217], v[104:107]
	v_mfma_f32_16x16x32_bf16 v[100:103], v[198:201], v[214:217], v[100:103]
	v_mfma_f32_16x16x32_bf16 v[88:91], v[190:193], v[222:225], v[88:91]
	v_mfma_f32_16x16x32_bf16 v[84:87], v[198:201], v[222:225], v[84:87]
	v_mfma_f32_16x16x32_bf16 v[72:75], v[190:193], v[230:233], v[72:75]
	v_mfma_f32_16x16x32_bf16 v[68:71], v[198:201], v[230:233], v[68:71]
	s_setprio 0
	s_barrier
; #define PG8_STAGE(bufoff, gbase, voff) do { _Pragma("unroll") for (int _i = 0; _i < 2; ++_i) \
;         __builtin_amdgcn_global_load_lds((const unsigned*)((const char*)(gbase) + (voff)[_i]), (PG8_LAS unsigned*)(lds + (bufoff) + ldsw + _i * 8192), 16, 0, 0); } while (0)
; #define PG8_LDA(dst, b, h) do { _Pragma("unroll") for (int m = 0; m < 4; ++m) _Pragma("unroll") for (int k = 0; k < 2; ++k) dst[m][k] = *(const PG8_LAS bf16x8*)(lds + PG8_SA(b, h) + aoff + m * 2048 + k * 1024); } while (0)
; #define PG8_WAIT_V(n) asm volatile("s_waitcnt vmcnt(" #n ")" ::: "memory")
; template <class Epi, class Sched, bool ALIGN_EPI = false, bool SP2 = false>
; __device__ __forceinline__ void gemm_phase(PG8_LAS unsigned char* lds, const Gemm g, const Sched& S, const Epi& E) {
;     ...
;         for (int t = 0; t < nt; t += 2) {
;             if constexpr (Epi::MIDSCALE) { if (t == (nt >> 1)) E.midscale(acc, cur, wr, fr, ui); }
;             const bool last = (t == nt - 2);
;             const char* a1 = cA + (size_t)(t >> 1) * apair + kstep;
;             const char* a2 = last ? nA : cA + (size_t)((t >> 1) + 1) * apair; const char* b2 = last ? nB : cB + (size_t)(t + 2) * kstep;
;             const char* a3 = a2 + kstep; const char* b3 = b2 + kstep;
;             if (last && has_next) S.a_ready(nxt, ui + 1);
;             if constexpr (SP2) {
;             PG8_LDB(B0, 0, 0); PG8_LDB(B1, 0, 1); PG8_SCHED; PG8_LDA(At, 0, 0); PG8_STAGE(PG8_SA(1, 1), a1 + hstepA, voffA);
;             PG8_WAIT_V(8); PG8_WAIT_L(0); PG8_BAR; PG8_MMA(0, 0, At, B0); PG8_MMA(0, 1, At, B1); PG8_BAR; PG8_SCHED;
;             PG8_LDA(At, 0, 1); PG8_STAGE(PG8_SB(0, 0), b2, voffB); PG8_STAGE(PG8_SB(0, 1), b2 + hstep, voffB); PG8_STAGE(PG8_SA(0, 0), a2, voffA);
;             PG8_WAIT_V(8); PG8_WAIT_L(0); PG8_BAR; PG8_MMA(1, 0, At, B0); PG8_MMA(1, 1, At, B1); PG8_BAR; PG8_SCHED;
;             PG8_LDB(B0, 1, 0); PG8_LDB(B1, 1, 1); PG8_SCHED; PG8_LDA(At, 1, 0); PG8_STAGE(PG8_SA(0, 1), a2 + hstepA, voffA);
;             PG8_WAIT_V(8); PG8_WAIT_L(0); PG8_BAR; PG8_MMA(0, 0, At, B0); PG8_MMA(0, 1, At, B1); PG8_BAR; PG8_SCHED;
;             PG8_LDA(At, 1, 1); PG8_STAGE(PG8_SB(1, 0), b3, voffB); PG8_STAGE(PG8_SB(1, 1), b3 + hstep, voffB); PG8_STAGE(PG8_SA(1, 0), a3, voffA);
;             PG8_WAIT_V(8); PG8_WAIT_L(0); PG8_BAR; PG8_MMA(1, 0, At, B0); PG8_MMA(1, 1, At, B1); PG8_BAR; PG8_SCHED;
	s_add_i32 s44, s86, s30
	v_lshl_add_u64 v[6:7], v[150:151], 0, s[48:49]
	s_mov_b32 m0, s44
	ds_read_b128 v[202:205], v156 offset:49152
	ds_read_b128 v[206:209], v156 offset:50176
	ds_read_b128 v[210:213], v156 offset:51200
	ds_read_b128 v[214:217], v156 offset:52224
	ds_read_b128 v[218:221], v156 offset:53248
	ds_read_b128 v[222:225], v156 offset:54272
	ds_read_b128 v[226:229], v156 offset:55296
	ds_read_b128 v[230:233], v156 offset:56320
	global_load_lds_dwordx4 v[6:7], off
	s_add_i32 m0, s44, 0x2000
	s_add_u32 s44, s66, 0x80080
	v_lshl_add_u64 v[6:7], v[166:167], 0, s[48:49]
	s_addc_u32 s45, s67, 0
	s_add_i32 s66, s87, s30
	global_load_lds_dwordx4 v[6:7], off
	v_lshl_add_u64 v[6:7], s[44:45], 0, v[134:135]
	s_mov_b32 m0, s66
	s_nop 0
	global_load_lds_dwordx4 v[6:7], off
	v_lshl_add_u64 v[6:7], s[44:45], 0, v[138:139]
	s_add_i32 m0, s66, 0x2000
	s_nop 0
	global_load_lds_dwordx4 v[6:7], off
	v_lshl_add_u64 v[6:7], v[170:171], 0, s[48:49]
	s_mov_b32 m0, s71
	s_nop 0
	global_load_lds_dwordx4 v[6:7], off
	v_lshl_add_u64 v[6:7], v[172:173], 0, s[48:49]
	s_mov_b32 m0, s72
	s_nop 0
	global_load_lds_dwordx4 v[6:7], off
	s_waitcnt vmcnt(8)
	s_waitcnt lgkmcnt(0)
	s_barrier
	s_setprio 1
	v_mfma_f32_16x16x32_bf16 v[64:67], v[158:161], v[202:205], v[64:67]
	v_mfma_f32_16x16x32_bf16 v[60:63], v[178:181], v[202:205], v[60:63]
	v_mfma_f32_16x16x32_bf16 v[48:51], v[158:161], v[210:213], v[48:51]
	v_mfma_f32_16x16x32_bf16 v[44:47], v[178:181], v[210:213], v[44:47]
	v_mfma_f32_16x16x32_bf16 v[32:35], v[158:161], v[218:221], v[32:35]
	v_mfma_f32_16x16x32_bf16 v[28:31], v[178:181], v[218:221], v[28:31]
	v_mfma_f32_16x16x32_bf16 v[16:19], v[158:161], v[226:229], v[16:19]
	v_mfma_f32_16x16x32_bf16 v[12:15], v[178:181], v[226:229], v[12:15]
	v_mfma_f32_16x16x32_bf16 v[64:67], v[162:165], v[206:209], v[64:67]
	v_mfma_f32_16x16x32_bf16 v[60:63], v[182:185], v[206:209], v[60:63]
	v_mfma_f32_16x16x32_bf16 v[48:51], v[162:165], v[214:217], v[48:51]
	v_mfma_f32_16x16x32_bf16 v[44:47], v[182:185], v[214:217], v[44:47]
	v_mfma_f32_16x16x32_bf16 v[32:35], v[162:165], v[222:225], v[32:35]
	v_mfma_f32_16x16x32_bf16 v[28:31], v[182:185], v[222:225], v[28:31]
	v_mfma_f32_16x16x32_bf16 v[16:19], v[162:165], v[230:233], v[16:19]
	v_mfma_f32_16x16x32_bf16 v[12:15], v[182:185], v[230:233], v[12:15]
	v_mfma_f32_16x16x32_bf16 v[56:59], v[186:189], v[202:205], v[56:59]
	v_mfma_f32_16x16x32_bf16 v[52:55], v[194:197], v[202:205], v[52:55]
	v_mfma_f32_16x16x32_bf16 v[40:43], v[186:189], v[210:213], v[40:43]
	v_mfma_f32_16x16x32_bf16 v[36:39], v[194:197], v[210:213], v[36:39]
	v_mfma_f32_16x16x32_bf16 v[24:27], v[186:189], v[218:221], v[24:27]
	v_mfma_f32_16x16x32_bf16 v[20:23], v[194:197], v[218:221], v[20:23]
	v_mfma_f32_16x16x32_bf16 v[6:9], v[186:189], v[226:229], v[8:11]
	v_mfma_f32_16x16x32_bf16 v[2:5], v[194:197], v[226:229], v[2:5]
	v_mfma_f32_16x16x32_bf16 v[56:59], v[190:193], v[206:209], v[56:59]
	v_mfma_f32_16x16x32_bf16 v[52:55], v[198:201], v[206:209], v[52:55]
	v_mfma_f32_16x16x32_bf16 v[40:43], v[190:193], v[214:217], v[40:43]
	v_mfma_f32_16x16x32_bf16 v[36:39], v[198:201], v[214:217], v[36:39]
	v_mfma_f32_16x16x32_bf16 v[24:27], v[190:193], v[222:225], v[24:27]
	v_mfma_f32_16x16x32_bf16 v[20:23], v[198:201], v[222:225], v[20:23]
	v_mfma_f32_16x16x32_bf16 v[8:11], v[190:193], v[230:233], v[6:9]
	v_mfma_f32_16x16x32_bf16 v[4:7], v[198:201], v[230:233], v[2:5]
	s_setprio 0
	s_barrier
	s_add_i32 s85, s85, 2
	s_add_u32 s83, s83, 0x100
	s_addc_u32 s84, s84, 0
	s_add_u32 s64, s64, 0x1080000
	s_addc_u32 s65, s65, 0
	s_cmp_gt_u32 s85, 29
	s_cbranch_scc1 .LBB0_392

;     __device__ __forceinline__ bool next(int i, Unit& u) const { if (i > 0) return false; u = u0; return true; }
; #define PG8_WAIT_V(n) asm volatile("s_waitcnt vmcnt(" #n ")" ::: "memory")
; template <class Epi, class Sched, bool ALIGN_EPI = false, bool SP2 = false>
; __device__ __forceinline__ void gemm_phase(PG8_LAS unsigned char* lds, const Gemm g, const Sched& S, const Epi& E) {
;     ...
;         PG8_WAIT_V(2); PG8_BAR;
;         PG8_STAGE(PG8_SB(1, 0), cB + kstep, voffB); PG8_STAGE(PG8_SA(1, 0), cA + kstep, voffA); PG8_STAGE(PG8_SB(1, 1), cB + hstep + kstep, voffB);
;         PG8_WAIT_V(6); PG8_BAR;
;     } else {
;         PG8_STAGE(PG8_SB(0, 0), cB, voffB); PG8_STAGE(PG8_SA(0, 0), cA, voffA); PG8_STAGE(PG8_SB(0, 1), cB + hstep, voffB); PG8_STAGE(PG8_SA(0, 1), cA + hstepA, voffA);
;         if (wr == 1) PG8_BAR;
;         PG8_WAIT_V(4); PG8_BAR;
;         PG8_STAGE(PG8_SB(1, 0), cB + kstep, voffB); PG8_STAGE(PG8_SA(1, 0), cA + kstep, voffA); PG8_STAGE(PG8_SB(1, 1), cB + hstep + kstep, voffB);
;         PG8_WAIT_V(6); PG8_BAR;
;     }
;     for (;;) {
;         const bool has_next = S.next(ui + 1, nxt);
;         const char* nA = has_next ? (const char*)g.A + (size_t)nxt.pm * tstepA : cA; const char* nB = has_next ? (const char*)g.Bt + (size_t)nxt.pn * tstep : cB;
;         for (int t = 0; t < nt; t += 2) {
;             if constexpr (Epi::MIDSCALE) { if (t == (nt >> 1)) E.midscale(acc, cur, wr, fr, ui); }
;             const bool last = (t == nt - 2);
;             const char* a1 = cA + (size_t)(t >> 1) * apair + kstep;
;             const char* a2 = last ? nA : cA + (size_t)((t >> 1) + 1) * apair; const char* b2 = last ? nB : cB + (size_t)(t + 2) * kstep;
;             const char* a3 = a2 + kstep; const char* b3 = b2 + kstep;
;             if (last && has_next) S.a_ready(nxt, ui + 1);
;             if constexpr (SP2) {
;             PG8_LDB(B0, 0, 0); PG8_LDB(B1, 0, 1); PG8_SCHED; PG8_LDA(At, 0, 0); PG8_STAGE(PG8_SA(1, 1), a1 + hstepA, voffA);
;             PG8_WAIT_V(8); PG8_WAIT_L(0); PG8_BAR; PG8_MMA(0, 0, At, B0); PG8_MMA(0, 1, At, B1); PG8_BAR; PG8_SCHED;
;             PG8_LDA(At, 0, 1); PG8_STAGE(PG8_SB(0, 0), b2, voffB); PG8_STAGE(PG8_SB(0, 1), b2 + hstep, voffB); PG8_STAGE(PG8_SA(0, 0), a2, voffA);
;             PG8_WAIT_V(8); PG8_WAIT_L(0); PG8_BAR; PG8_MMA(1, 0, At, B0); PG8_MMA(1, 1, At, B1); PG8_BAR; PG8_SCHED;
.LBB0_417:
	s_add_i32 s42, 0, 0x18000
	s_and_b32 s0, s0, 3
	s_add_i32 s30, s42, s12
	s_lshl_b32 s7, s0, 12
	s_lshl_b32 s13, s6, 13
	v_lshl_add_u64 v[18:19], v[2:3], 0, s[48:49]
	s_mov_b32 m0, s30
	s_add_i32 s46, s30, 0x2000
	s_add_i32 s35, s16, 0x8000
	s_add_i32 s47, s16, 0xa000
	s_waitcnt vmcnt(2)
	s_barrier
	global_load_lds_dwordx4 v[18:19], off
	v_lshl_add_u64 v[22:23], v[4:5], 0, s[48:49]
	s_mov_b32 m0, s46
	s_add_u32 s26, s4, 0x80080
	global_load_lds_dwordx4 v[22:23], off
	v_lshl_add_u64 v[16:17], v[20:21], 0, s[48:49]
	s_mov_b32 m0, s35
	s_addc_u32 s27, s5, 0
	s_add_i32 s43, 0, 0x1c000
	global_load_lds_dwordx4 v[16:17], off
	v_lshl_add_u64 v[24:25], v[28:29], 0, s[48:49]
	s_mov_b32 m0, s47
	s_add_i32 s50, s43, s12
	global_load_lds_dwordx4 v[24:25], off
	v_lshl_add_u64 v[30:31], s[26:27], 0, v[0:1]
	s_mov_b32 m0, s50
	s_add_i32 s51, s50, 0x2000
	global_load_lds_dwordx4 v[30:31], off
	v_lshl_add_u64 v[32:33], s[26:27], 0, v[34:35]
	s_mov_b32 m0, s51
	v_and_b32_e32 v6, 15, v36
	global_load_lds_dwordx4 v[32:33], off
	v_and_b32_e32 v134, 48, v36
	v_lshlrev_b32_e32 v7, 2, v36
	v_lshl_or_b32 v132, s6, 6, v6
	v_lshl_or_b32 v6, v6, 6, v134
	v_and_b32_e32 v7, 32, v7
	v_bitop3_b32 v36, v6, s7, v7 bitop3:0xde
	s_add_i32 s58, 0, 0x10000
	s_add_i32 s60, 0, 0x14000
	v_add_u32_e32 v135, s42, v36
	s_add_u32 s42, s20, 0x1080000
	v_add_u32_e32 v177, s43, v36
	s_addc_u32 s43, s21, 0
	s_add_u32 s6, s20, 0x1080080
	s_addc_u32 s7, s21, 0
	v_add_u32_e32 v128, s58, v36
	s_add_u32 s64, s20, 0x8080
	s_waitcnt vmcnt(6)
	s_barrier
	v_add_u32_e32 v129, s60, v36
	s_addc_u32 s65, s21, 0
	s_add_i32 s58, s58, s12
	ds_read_b128 v[36:39], v128
	ds_read_b128 v[40:43], v128 offset:1024
	ds_read_b128 v[44:47], v128 offset:2048
	ds_read_b128 v[48:51], v128 offset:3072
	ds_read_b128 v[52:55], v129
	ds_read_b128 v[56:59], v129 offset:1024
	ds_read_b128 v[60:63], v129 offset:2048
	ds_read_b128 v[64:67], v129 offset:3072
	s_add_i32 s63, s16, 0xc000
	s_add_i32 s62, s16, 0xe000
	s_add_i32 s53, s58, 0x2000
	s_add_u32 s44, s4, 0x80100
	s_addc_u32 s45, s5, 0
	s_add_i32 s60, s60, s12
	s_add_i32 s59, s60, 0x2000
	s_add_u32 s26, s20, 0x1088000
	s_addc_u32 s27, s21, 0
	s_add_u32 s12, s4, 0x80180
	v_bitop3_b32 v6, v6, s13, v7 bitop3:0xde
	s_addc_u32 s13, s5, 0
	s_add_u32 s4, s20, 0x1088080
	s_addc_u32 s5, s21, 0
	v_add_u32_e32 v133, 0, v6
	s_cmpk_gt_u32 s61, 0xff
	s_mov_b32 m0, s63
	v_lshl_add_u64 v[6:7], s[64:65], 0, v[8:9]
	ds_read_b128 v[68:71], v133
	ds_read_b128 v[72:75], v133 offset:1024
	ds_read_b128 v[76:79], v133 offset:2048
	ds_read_b128 v[80:83], v133 offset:3072
	ds_read_b128 v[84:87], v133 offset:4096
	ds_read_b128 v[88:91], v133 offset:5120
	ds_read_b128 v[92:95], v133 offset:6144
	ds_read_b128 v[96:99], v133 offset:7168
	global_load_lds_dwordx4 v[6:7], off
	v_lshl_add_u64 v[6:7], s[64:65], 0, v[26:27]
	s_mov_b32 m0, s62
	s_nop 0
	global_load_lds_dwordx4 v[6:7], off
	s_waitcnt vmcnt(8)
	s_waitcnt lgkmcnt(0)
	s_barrier
	s_setprio 1
	v_mfma_f32_16x16x32_bf16 v[100:103], v[36:39], v[68:71], 0
	v_mfma_f32_16x16x32_bf16 v[104:107], v[44:47], v[68:71], 0
	v_mfma_f32_16x16x32_bf16 v[108:111], v[36:39], v[76:79], 0
	v_mfma_f32_16x16x32_bf16 v[112:115], v[44:47], v[76:79], 0
	v_mfma_f32_16x16x32_bf16 v[116:119], v[36:39], v[84:87], 0
	v_mfma_f32_16x16x32_bf16 v[120:123], v[44:47], v[84:87], 0
	v_mfma_f32_16x16x32_bf16 v[124:127], v[36:39], v[92:95], 0
	v_mfma_f32_16x16x32_bf16 v[136:139], v[44:47], v[92:95], 0
	v_mfma_f32_16x16x32_bf16 v[100:103], v[40:43], v[72:75], v[100:103]
	v_mfma_f32_16x16x32_bf16 v[104:107], v[48:51], v[72:75], v[104:107]
	v_mfma_f32_16x16x32_bf16 v[108:111], v[40:43], v[80:83], v[108:111]
	v_mfma_f32_16x16x32_bf16 v[112:115], v[48:51], v[80:83], v[112:115]
	v_mfma_f32_16x16x32_bf16 v[116:119], v[40:43], v[88:91], v[116:119]
	v_mfma_f32_16x16x32_bf16 v[120:123], v[48:51], v[88:91], v[120:123]
	v_mfma_f32_16x16x32_bf16 v[124:127], v[40:43], v[96:99], v[124:127]
	v_mfma_f32_16x16x32_bf16 v[136:139], v[48:51], v[96:99], v[136:139]
	v_mfma_f32_16x16x32_bf16 v[140:143], v[52:55], v[68:71], 0
	v_mfma_f32_16x16x32_bf16 v[68:71], v[60:63], v[68:71], 0
	v_mfma_f32_16x16x32_bf16 v[140:143], v[56:59], v[72:75], v[140:143]
	v_mfma_f32_16x16x32_bf16 v[68:71], v[64:67], v[72:75], v[68:71]
	v_mfma_f32_16x16x32_bf16 v[72:75], v[52:55], v[76:79], 0
	v_mfma_f32_16x16x32_bf16 v[76:79], v[60:63], v[76:79], 0
	v_mfma_f32_16x16x32_bf16 v[72:75], v[56:59], v[80:83], v[72:75]
	v_mfma_f32_16x16x32_bf16 v[76:79], v[64:67], v[80:83], v[76:79]
	v_mfma_f32_16x16x32_bf16 v[80:83], v[52:55], v[84:87], 0
	v_mfma_f32_16x16x32_bf16 v[84:87], v[60:63], v[84:87], 0
	v_mfma_f32_16x16x32_bf16 v[80:83], v[56:59], v[88:91], v[80:83]
	v_mfma_f32_16x16x32_bf16 v[84:87], v[64:67], v[88:91], v[84:87]
	v_mfma_f32_16x16x32_bf16 v[88:91], v[52:55], v[92:95], 0
	v_mfma_f32_16x16x32_bf16 v[92:95], v[60:63], v[92:95], 0
	v_mfma_f32_16x16x32_bf16 v[88:91], v[56:59], v[96:99], v[88:91]
	v_mfma_f32_16x16x32_bf16 v[92:95], v[64:67], v[96:99], v[92:95]
	s_setprio 0
	s_barrier
	s_mov_b64 s[20:21], 0x100
	s_mov_b32 m0, s58
	v_lshl_add_u64 v[6:7], v[2:3], 0, s[20:21]
	ds_read_b128 v[96:99], v133 offset:16384
	ds_read_b128 v[144:147], v133 offset:17408
	ds_read_b128 v[154:157], v133 offset:18432
	ds_read_b128 v[158:161], v133 offset:19456
	ds_read_b128 v[162:165], v133 offset:20480
	ds_read_b128 v[178:181], v133 offset:21504
	ds_read_b128 v[182:185], v133 offset:22528
	ds_read_b128 v[186:189], v133 offset:23552
	global_load_lds_dwordx4 v[6:7], off
	v_lshl_add_u64 v[6:7], v[4:5], 0, s[20:21]
	s_mov_b32 m0, s53
	s_nop 0
	global_load_lds_dwordx4 v[6:7], off
	v_lshl_add_u64 v[6:7], s[44:45], 0, v[0:1]
	s_mov_b32 m0, s60
	s_nop 0
	global_load_lds_dwordx4 v[6:7], off
	v_lshl_add_u64 v[6:7], s[44:45], 0, v[34:35]
	s_mov_b32 m0, s59
	s_nop 0
	global_load_lds_dwordx4 v[6:7], off
	v_lshl_add_u64 v[6:7], s[42:43], 0, v[8:9]
	s_mov_b32 m0, s16
	s_nop 0
	global_load_lds_dwordx4 v[6:7], off
	v_lshl_add_u64 v[6:7], s[42:43], 0, v[26:27]
	s_mov_b32 m0, s52
	s_nop 0
	global_load_lds_dwordx4 v[6:7], off
	s_waitcnt vmcnt(8)
	s_waitcnt lgkmcnt(0)
	s_barrier
; #define PG8_STAGE(bufoff, gbase, voff) do { _Pragma("unroll") for (int _i = 0; _i < 2; ++_i) \
;         __builtin_amdgcn_global_load_lds((const unsigned*)((const char*)(gbase) + (voff)[_i]), (PG8_LAS unsigned*)(lds + (bufoff) + ldsw + _i * 8192), 16, 0, 0); } while (0)
; #define PG8_LDA(dst, b, h) do { _Pragma("unroll") for (int m = 0; m < 4; ++m) _Pragma("unroll") for (int k = 0; k < 2; ++k) dst[m][k] = *(const PG8_LAS bf16x8*)(lds + PG8_SA(b, h) + aoff + m * 2048 + k * 1024); } while (0)
; #define PG8_LDB(dst, b, h) do { _Pragma("unroll") for (int n = 0; n < 2; ++n) _Pragma("unroll") for (int k = 0; k < 2; ++k) dst[n][k] = *(const PG8_LAS bf16x8*)(lds + PG8_SB(b, h) + boff + n * 2048 + k * 1024); } while (0)
; #define PG8_MMA(ai, bj, At, Bt) do { __builtin_amdgcn_s_setprio(1); _Pragma("unroll") for (int m = 0; m < 4; ++m) _Pragma("unroll") for (int n = 0; n < 2; ++n) _Pragma("unroll") for (int k = 0; k < 2; ++k) \
;         acc[ai][bj][m][n] = __builtin_amdgcn_mfma_f32_16x16x32_bf16(Bt[n][k], At[m][k], acc[ai][bj][m][n], 0, 0, 0); __builtin_amdgcn_s_setprio(0); } while (0)
; #define PG8_WAIT_V(n) asm volatile("s_waitcnt vmcnt(" #n ")" ::: "memory")
; #define PG8_WAIT_L(n) asm volatile("s_waitcnt lgkmcnt(" #n ")" ::: "memory")
; #define PG8_BAR __builtin_amdgcn_s_barrier()
; #define PG8_SCHED __builtin_amdgcn_sched_barrier(0)
; template <class Epi, class Sched, bool ALIGN_EPI = false, bool SP2 = false>
; __device__ __forceinline__ void gemm_phase(PG8_LAS unsigned char* lds, const Gemm g, const Sched& S, const Epi& E) {
;     ...
;             PG8_WAIT_V(8); PG8_WAIT_L(0); PG8_BAR; PG8_MMA(1, 0, At, B0); PG8_MMA(1, 1, At, B1); PG8_BAR; PG8_SCHED;
;             PG8_LDB(B0, 1, 0); PG8_LDB(B1, 1, 1); PG8_SCHED; PG8_LDA(At, 1, 0); PG8_STAGE(PG8_SA(0, 1), a2 + hstepA, voffA);
;             PG8_WAIT_V(8); PG8_WAIT_L(0); PG8_BAR; PG8_MMA(0, 0, At, B0); PG8_MMA(0, 1, At, B1); PG8_BAR; PG8_SCHED;
	s_setprio 1
	v_mfma_f32_16x16x32_bf16 v[190:193], v[36:39], v[96:99], 0
	v_mfma_f32_16x16x32_bf16 v[198:201], v[36:39], v[154:157], 0
	v_mfma_f32_16x16x32_bf16 v[206:209], v[36:39], v[162:165], 0
	v_mfma_f32_16x16x32_bf16 v[36:39], v[36:39], v[182:185], 0
	v_mfma_f32_16x16x32_bf16 v[190:193], v[40:43], v[144:147], v[190:193]
	v_mfma_f32_16x16x32_bf16 v[198:201], v[40:43], v[158:161], v[198:201]
	v_mfma_f32_16x16x32_bf16 v[206:209], v[40:43], v[178:181], v[206:209]
	v_mfma_f32_16x16x32_bf16 v[36:39], v[40:43], v[186:189], v[36:39]
	v_mfma_f32_16x16x32_bf16 v[40:43], v[44:47], v[182:185], 0
	v_mfma_f32_16x16x32_bf16 v[194:197], v[44:47], v[96:99], 0
	v_mfma_f32_16x16x32_bf16 v[202:205], v[44:47], v[154:157], 0
	v_mfma_f32_16x16x32_bf16 v[210:213], v[44:47], v[162:165], 0
	v_mfma_f32_16x16x32_bf16 v[40:43], v[48:51], v[186:189], v[40:43]
	v_mfma_f32_16x16x32_bf16 v[194:197], v[48:51], v[144:147], v[194:197]
	v_mfma_f32_16x16x32_bf16 v[202:205], v[48:51], v[158:161], v[202:205]
	v_mfma_f32_16x16x32_bf16 v[210:213], v[48:51], v[178:181], v[210:213]
	v_mfma_f32_16x16x32_bf16 v[44:47], v[52:55], v[96:99], 0
	v_mfma_f32_16x16x32_bf16 v[48:51], v[60:63], v[96:99], 0
	v_mfma_f32_16x16x32_bf16 v[44:47], v[56:59], v[144:147], v[44:47]
	v_mfma_f32_16x16x32_bf16 v[48:51], v[64:67], v[144:147], v[48:51]
	v_mfma_f32_16x16x32_bf16 v[96:99], v[52:55], v[154:157], 0
	v_mfma_f32_16x16x32_bf16 v[144:147], v[60:63], v[154:157], 0
	v_mfma_f32_16x16x32_bf16 v[154:157], v[52:55], v[162:165], 0
	v_mfma_f32_16x16x32_bf16 v[52:55], v[52:55], v[182:185], 0
	v_mfma_f32_16x16x32_bf16 v[96:99], v[56:59], v[158:161], v[96:99]
	v_mfma_f32_16x16x32_bf16 v[154:157], v[56:59], v[178:181], v[154:157]
	v_mfma_f32_16x16x32_bf16 v[52:55], v[56:59], v[186:189], v[52:55]
	v_mfma_f32_16x16x32_bf16 v[56:59], v[60:63], v[182:185], 0
	v_mfma_f32_16x16x32_bf16 v[144:147], v[64:67], v[158:161], v[144:147]
	v_mfma_f32_16x16x32_bf16 v[158:161], v[60:63], v[162:165], 0
	v_mfma_f32_16x16x32_bf16 v[56:59], v[64:67], v[186:189], v[56:59]
	v_mfma_f32_16x16x32_bf16 v[158:161], v[64:67], v[178:181], v[158:161]
	s_setprio 0
	s_barrier
	ds_read_b128 v[60:63], v135
	ds_read_b128 v[64:67], v135 offset:1024
	ds_read_b128 v[162:165], v135 offset:2048
	ds_read_b128 v[178:181], v135 offset:3072
	ds_read_b128 v[182:185], v177
	ds_read_b128 v[186:189], v177 offset:1024
	ds_read_b128 v[214:217], v177 offset:2048
	ds_read_b128 v[218:221], v177 offset:3072
	s_mov_b32 m0, s17
	v_lshl_add_u64 v[6:7], s[26:27], 0, v[8:9]
	ds_read_b128 v[222:225], v133 offset:32768
	ds_read_b128 v[226:229], v133 offset:33792
	ds_read_b128 v[230:233], v133 offset:34816
	ds_read_b128 v[234:237], v133 offset:35840
	ds_read_b128 v[238:241], v133 offset:36864
	ds_read_b128 v[242:245], v133 offset:37888
	ds_read_b128 v[246:249], v133 offset:38912
	ds_read_b128 v[250:253], v133 offset:39936
	global_load_lds_dwordx4 v[6:7], off
	v_lshl_add_u64 v[6:7], s[26:27], 0, v[26:27]
	s_mov_b32 m0, s28
	s_nop 0
	global_load_lds_dwordx4 v[6:7], off
	s_waitcnt vmcnt(8)
	s_waitcnt lgkmcnt(0)
	s_barrier
	s_setprio 1
	v_mfma_f32_16x16x32_bf16 v[100:103], v[60:63], v[222:225], v[100:103]
	v_mfma_f32_16x16x32_bf16 v[104:107], v[162:165], v[222:225], v[104:107]
	v_mfma_f32_16x16x32_bf16 v[108:111], v[60:63], v[230:233], v[108:111]
	v_mfma_f32_16x16x32_bf16 v[112:115], v[162:165], v[230:233], v[112:115]
	v_mfma_f32_16x16x32_bf16 v[116:119], v[60:63], v[238:241], v[116:119]
	v_mfma_f32_16x16x32_bf16 v[120:123], v[162:165], v[238:241], v[120:123]
	v_mfma_f32_16x16x32_bf16 v[124:127], v[60:63], v[246:249], v[124:127]
	v_mfma_f32_16x16x32_bf16 v[136:139], v[162:165], v[246:249], v[136:139]
	v_mfma_f32_16x16x32_bf16 v[100:103], v[64:67], v[226:229], v[100:103]
	v_mfma_f32_16x16x32_bf16 v[104:107], v[178:181], v[226:229], v[104:107]
	v_mfma_f32_16x16x32_bf16 v[108:111], v[64:67], v[234:237], v[108:111]
	v_mfma_f32_16x16x32_bf16 v[112:115], v[178:181], v[234:237], v[112:115]
	v_mfma_f32_16x16x32_bf16 v[116:119], v[64:67], v[242:245], v[116:119]
	v_mfma_f32_16x16x32_bf16 v[120:123], v[178:181], v[242:245], v[120:123]
	v_mfma_f32_16x16x32_bf16 v[124:127], v[64:67], v[250:253], v[124:127]
	v_mfma_f32_16x16x32_bf16 v[136:139], v[178:181], v[250:253], v[136:139]
	v_mfma_f32_16x16x32_bf16 v[68:71], v[214:217], v[222:225], v[68:71]
	v_mfma_f32_16x16x32_bf16 v[80:83], v[182:185], v[238:241], v[80:83]
	v_mfma_f32_16x16x32_bf16 v[84:87], v[214:217], v[238:241], v[84:87]
	v_mfma_f32_16x16x32_bf16 v[88:91], v[182:185], v[246:249], v[88:91]
	v_mfma_f32_16x16x32_bf16 v[92:95], v[214:217], v[246:249], v[92:95]
	v_mfma_f32_16x16x32_bf16 v[140:143], v[182:185], v[222:225], v[140:143]
	v_mfma_f32_16x16x32_bf16 v[68:71], v[218:221], v[226:229], v[68:71]
	v_mfma_f32_16x16x32_bf16 v[72:75], v[182:185], v[230:233], v[72:75]
	v_mfma_f32_16x16x32_bf16 v[76:79], v[214:217], v[230:233], v[76:79]
	v_mfma_f32_16x16x32_bf16 v[80:83], v[186:189], v[242:245], v[80:83]
	v_mfma_f32_16x16x32_bf16 v[84:87], v[218:221], v[242:245], v[84:87]
	v_mfma_f32_16x16x32_bf16 v[88:91], v[186:189], v[250:253], v[88:91]
	v_mfma_f32_16x16x32_bf16 v[92:95], v[218:221], v[250:253], v[92:95]
	v_mfma_f32_16x16x32_bf16 v[140:143], v[186:189], v[226:229], v[140:143]
	v_mfma_f32_16x16x32_bf16 v[72:75], v[186:189], v[234:237], v[72:75]
	v_mfma_f32_16x16x32_bf16 v[76:79], v[218:221], v[234:237], v[76:79]
	s_setprio 0
	s_barrier
; #define PG8_STAGE(bufoff, gbase, voff) do { _Pragma("unroll") for (int _i = 0; _i < 2; ++_i) \
;         __builtin_amdgcn_global_load_lds((const unsigned*)((const char*)(gbase) + (voff)[_i]), (PG8_LAS unsigned*)(lds + (bufoff) + ldsw + _i * 8192), 16, 0, 0); } while (0)
; #define PG8_LDA(dst, b, h) do { _Pragma("unroll") for (int m = 0; m < 4; ++m) _Pragma("unroll") for (int k = 0; k < 2; ++k) dst[m][k] = *(const PG8_LAS bf16x8*)(lds + PG8_SA(b, h) + aoff + m * 2048 + k * 1024); } while (0)
; #define PG8_LDB(dst, b, h) do { _Pragma("unroll") for (int n = 0; n < 2; ++n) _Pragma("unroll") for (int k = 0; k < 2; ++k) dst[n][k] = *(const PG8_LAS bf16x8*)(lds + PG8_SB(b, h) + boff + n * 2048 + k * 1024); } while (0)
; #define PG8_MMA(ai, bj, At, Bt) do { __builtin_amdgcn_s_setprio(1); _Pragma("unroll") for (int m = 0; m < 4; ++m) _Pragma("unroll") for (int n = 0; n < 2; ++n) _Pragma("unroll") for (int k = 0; k < 2; ++k) \
;         acc[ai][bj][m][n] = __builtin_amdgcn_mfma_f32_16x16x32_bf16(Bt[n][k], At[m][k], acc[ai][bj][m][n], 0, 0, 0); __builtin_amdgcn_s_setprio(0); } while (0)
; #define PG8_WAIT_V(n) asm volatile("s_waitcnt vmcnt(" #n ")" ::: "memory")
; #define PG8_WAIT_L(n) asm volatile("s_waitcnt lgkmcnt(" #n ")" ::: "memory")
; #define PG8_BAR __builtin_amdgcn_s_barrier()
; #define PG8_SCHED __builtin_amdgcn_sched_barrier(0)
; template <class Epi, class Sched, bool ALIGN_EPI = false, bool SP2 = false>
; __device__ __forceinline__ void gemm_phase(PG8_LAS unsigned char* lds, const Gemm g, const Sched& S, const Epi& E) {
;     ...
;             PG8_LDB(B0, 0, 0); PG8_LDB(B1, 0, 1); PG8_SCHED; PG8_LDA(At, 0, 0); PG8_STAGE(PG8_SA(1, 1), a1 + hstepA, voffA);
;             PG8_WAIT_V(8); PG8_WAIT_L(0); PG8_BAR; PG8_MMA(0, 0, At, B0); PG8_MMA(0, 1, At, B1); PG8_BAR; PG8_SCHED;
;     ...
;             PG8_LDA(At, 1, 1); PG8_STAGE(PG8_SB(1, 0), b3, voffB); PG8_STAGE(PG8_SB(1, 1), b3 + hstep, voffB); PG8_STAGE(PG8_SA(1, 0), a3, voffA);
;             PG8_WAIT_V(8); PG8_WAIT_L(0); PG8_BAR; PG8_MMA(1, 0, At, B0); PG8_MMA(1, 1, At, B1); PG8_BAR; PG8_SCHED;
	s_mov_b64 s[20:21], 0x180
	s_mov_b32 m0, s30
	v_lshl_add_u64 v[6:7], v[2:3], 0, s[20:21]
	ds_read_b128 v[222:225], v133 offset:49152
	ds_read_b128 v[226:229], v133 offset:50176
	ds_read_b128 v[230:233], v133 offset:51200
	ds_read_b128 v[234:237], v133 offset:52224
	ds_read_b128 v[238:241], v133 offset:53248
	ds_read_b128 v[242:245], v133 offset:54272
	ds_read_b128 v[246:249], v133 offset:55296
	ds_read_b128 v[250:253], v133 offset:56320
	global_load_lds_dwordx4 v[6:7], off
	v_lshl_add_u64 v[6:7], v[4:5], 0, s[20:21]
	s_mov_b32 m0, s46
	s_nop 0
	global_load_lds_dwordx4 v[6:7], off
	v_lshl_add_u64 v[6:7], s[12:13], 0, v[0:1]
	s_mov_b32 m0, s50
	s_nop 0
	global_load_lds_dwordx4 v[6:7], off
	v_lshl_add_u64 v[6:7], s[12:13], 0, v[34:35]
	s_mov_b32 m0, s51
	s_nop 0
	global_load_lds_dwordx4 v[6:7], off
	v_lshl_add_u64 v[6:7], s[6:7], 0, v[8:9]
	s_mov_b32 m0, s35
	s_nop 0
	global_load_lds_dwordx4 v[6:7], off
	v_lshl_add_u64 v[6:7], s[6:7], 0, v[26:27]
	s_mov_b32 m0, s47
	s_nop 0
	global_load_lds_dwordx4 v[6:7], off
	s_waitcnt vmcnt(8)
	s_waitcnt lgkmcnt(0)
	s_barrier
	s_setprio 1
	v_mfma_f32_16x16x32_bf16 v[34:37], v[60:63], v[246:249], v[36:39]
	v_mfma_f32_16x16x32_bf16 v[38:41], v[162:165], v[246:249], v[40:43]
	v_mfma_f32_16x16x32_bf16 v[190:193], v[60:63], v[222:225], v[190:193]
	v_mfma_f32_16x16x32_bf16 v[194:197], v[162:165], v[222:225], v[194:197]
	v_mfma_f32_16x16x32_bf16 v[198:201], v[60:63], v[230:233], v[198:201]
	v_mfma_f32_16x16x32_bf16 v[202:205], v[162:165], v[230:233], v[202:205]
	v_mfma_f32_16x16x32_bf16 v[206:209], v[60:63], v[238:241], v[206:209]
	v_mfma_f32_16x16x32_bf16 v[210:213], v[162:165], v[238:241], v[210:213]
	v_mfma_f32_16x16x32_bf16 v[34:37], v[64:67], v[250:253], v[34:37]
	v_mfma_f32_16x16x32_bf16 v[38:41], v[178:181], v[250:253], v[38:41]
	v_mfma_f32_16x16x32_bf16 v[190:193], v[64:67], v[226:229], v[190:193]
	v_mfma_f32_16x16x32_bf16 v[194:197], v[178:181], v[226:229], v[194:197]
	v_mfma_f32_16x16x32_bf16 v[198:201], v[64:67], v[234:237], v[198:201]
	v_mfma_f32_16x16x32_bf16 v[202:205], v[178:181], v[234:237], v[202:205]
	v_mfma_f32_16x16x32_bf16 v[206:209], v[64:67], v[242:245], v[206:209]
	v_mfma_f32_16x16x32_bf16 v[210:213], v[178:181], v[242:245], v[210:213]
	v_mfma_f32_16x16x32_bf16 v[42:45], v[182:185], v[222:225], v[44:47]
	v_mfma_f32_16x16x32_bf16 v[46:49], v[214:217], v[222:225], v[48:51]
	v_mfma_f32_16x16x32_bf16 v[60:63], v[182:185], v[230:233], v[96:99]
	v_mfma_f32_16x16x32_bf16 v[64:67], v[214:217], v[230:233], v[144:147]
	v_mfma_f32_16x16x32_bf16 v[96:99], v[182:185], v[238:241], v[154:157]
	v_mfma_f32_16x16x32_bf16 v[50:53], v[182:185], v[246:249], v[52:55]
	v_mfma_f32_16x16x32_bf16 v[54:57], v[214:217], v[246:249], v[56:59]
	v_mfma_f32_16x16x32_bf16 v[42:45], v[186:189], v[226:229], v[42:45]
	v_mfma_f32_16x16x32_bf16 v[46:49], v[218:221], v[226:229], v[46:49]
	v_mfma_f32_16x16x32_bf16 v[60:63], v[186:189], v[234:237], v[60:63]
	v_mfma_f32_16x16x32_bf16 v[64:67], v[218:221], v[234:237], v[64:67]
	v_mfma_f32_16x16x32_bf16 v[96:99], v[186:189], v[242:245], v[96:99]
	v_mfma_f32_16x16x32_bf16 v[144:147], v[214:217], v[238:241], v[158:161]
	v_mfma_f32_16x16x32_bf16 v[50:53], v[186:189], v[250:253], v[50:53]
	v_mfma_f32_16x16x32_bf16 v[54:57], v[218:221], v[250:253], v[54:57]
	v_mfma_f32_16x16x32_bf16 v[144:147], v[218:221], v[242:245], v[144:147]
	s_setprio 0
	s_barrier
	ds_read_b128 v[154:157], v128
	ds_read_b128 v[158:161], v128 offset:1024
	ds_read_b128 v[162:165], v128 offset:2048
	ds_read_b128 v[178:181], v128 offset:3072
	ds_read_b128 v[182:185], v129
	ds_read_b128 v[186:189], v129 offset:1024
	ds_read_b128 v[214:217], v129 offset:2048
	ds_read_b128 v[218:221], v129 offset:3072
	s_mov_b32 m0, s63
	v_lshl_add_u64 v[6:7], s[4:5], 0, v[8:9]
	ds_read_b128 v[222:225], v133
	ds_read_b128 v[226:229], v133 offset:1024
	ds_read_b128 v[230:233], v133 offset:2048
	ds_read_b128 v[234:237], v133 offset:3072
	ds_read_b128 v[238:241], v133 offset:4096
	ds_read_b128 v[242:245], v133 offset:5120
	ds_read_b128 v[246:249], v133 offset:6144
	ds_read_b128 v[250:253], v133 offset:7168
	global_load_lds_dwordx4 v[6:7], off
	v_lshl_add_u64 v[6:7], s[4:5], 0, v[26:27]
	s_mov_b32 m0, s62
	s_nop 0
	global_load_lds_dwordx4 v[6:7], off
	s_waitcnt vmcnt(8)
	s_waitcnt lgkmcnt(0)
	s_barrier
	s_setprio 1
	v_mfma_f32_16x16x32_bf16 v[112:115], v[162:165], v[230:233], v[112:115]
	v_mfma_f32_16x16x32_bf16 v[170:173], v[178:181], v[234:237], v[112:115]
	v_mfma_f32_16x16x32_bf16 v[112:115], v[154:157], v[238:241], v[116:119]
	v_mfma_f32_16x16x32_bf16 v[148:151], v[158:161], v[242:245], v[112:115]
	v_mfma_f32_16x16x32_bf16 v[112:115], v[162:165], v[238:241], v[120:123]
	v_mfma_f32_16x16x32_bf16 v[128:131], v[178:181], v[242:245], v[112:115]
	v_mfma_f32_16x16x32_bf16 v[112:115], v[154:157], v[246:249], v[124:127]
	v_mfma_f32_16x16x32_bf16 v[100:103], v[154:157], v[222:225], v[100:103]
	v_mfma_f32_16x16x32_bf16 v[104:107], v[162:165], v[222:225], v[104:107]
	v_mfma_f32_16x16x32_bf16 v[108:111], v[154:157], v[230:233], v[108:111]
	v_mfma_f32_16x16x32_bf16 v[122:125], v[158:161], v[250:253], v[112:115]
	v_mfma_f32_16x16x32_bf16 v[112:115], v[162:165], v[246:249], v[136:139]
	v_mfma_f32_16x16x32_bf16 v[100:103], v[158:161], v[226:229], v[100:103]
	v_mfma_f32_16x16x32_bf16 v[104:107], v[178:181], v[226:229], v[104:107]
	v_mfma_f32_16x16x32_bf16 v[108:111], v[158:161], v[234:237], v[108:111]
	v_mfma_f32_16x16x32_bf16 v[136:139], v[178:181], v[250:253], v[112:115]
	v_mfma_f32_16x16x32_bf16 v[72:75], v[182:185], v[230:233], v[72:75]
	v_mfma_f32_16x16x32_bf16 v[112:115], v[182:185], v[222:225], v[140:143]
	v_mfma_f32_16x16x32_bf16 v[68:71], v[214:217], v[222:225], v[68:71]
	v_mfma_f32_16x16x32_bf16 v[222:225], v[186:189], v[234:237], v[72:75]
	v_mfma_f32_16x16x32_bf16 v[72:75], v[214:217], v[230:233], v[76:79]
	v_mfma_f32_16x16x32_bf16 v[140:143], v[186:189], v[226:229], v[112:115]
	v_mfma_f32_16x16x32_bf16 v[68:71], v[218:221], v[226:229], v[68:71]
	v_mfma_f32_16x16x32_bf16 v[226:229], v[218:221], v[234:237], v[72:75]
	v_mfma_f32_16x16x32_bf16 v[72:75], v[182:185], v[238:241], v[80:83]
	v_mfma_f32_16x16x32_bf16 v[230:233], v[186:189], v[242:245], v[72:75]
	v_mfma_f32_16x16x32_bf16 v[72:75], v[214:217], v[238:241], v[84:87]
	v_mfma_f32_16x16x32_bf16 v[234:237], v[218:221], v[242:245], v[72:75]
	v_mfma_f32_16x16x32_bf16 v[72:75], v[182:185], v[246:249], v[88:91]
	v_mfma_f32_16x16x32_bf16 v[238:241], v[186:189], v[250:253], v[72:75]
	v_mfma_f32_16x16x32_bf16 v[72:75], v[214:217], v[246:249], v[92:95]
	v_mfma_f32_16x16x32_bf16 v[242:245], v[218:221], v[250:253], v[72:75]
	s_setprio 0
	s_barrier
; #define PG8_STAGE(bufoff, gbase, voff) do { _Pragma("unroll") for (int _i = 0; _i < 2; ++_i) \
;         __builtin_amdgcn_global_load_lds((const unsigned*)((const char*)(gbase) + (voff)[_i]), (PG8_LAS unsigned*)(lds + (bufoff) + ldsw + _i * 8192), 16, 0, 0); } while (0)
; #define PG8_LDA(dst, b, h) do { _Pragma("unroll") for (int m = 0; m < 4; ++m) _Pragma("unroll") for (int k = 0; k < 2; ++k) dst[m][k] = *(const PG8_LAS bf16x8*)(lds + PG8_SA(b, h) + aoff + m * 2048 + k * 1024); } while (0)
; #define PG8_LDB(dst, b, h) do { _Pragma("unroll") for (int n = 0; n < 2; ++n) _Pragma("unroll") for (int k = 0; k < 2; ++k) dst[n][k] = *(const PG8_LAS bf16x8*)(lds + PG8_SB(b, h) + boff + n * 2048 + k * 1024); } while (0)
; #define PG8_MMA(ai, bj, At, Bt) do { __builtin_amdgcn_s_setprio(1); _Pragma("unroll") for (int m = 0; m < 4; ++m) _Pragma("unroll") for (int n = 0; n < 2; ++n) _Pragma("unroll") for (int k = 0; k < 2; ++k) \
;         acc[ai][bj][m][n] = __builtin_amdgcn_mfma_f32_16x16x32_bf16(Bt[n][k], At[m][k], acc[ai][bj][m][n], 0, 0, 0); __builtin_amdgcn_s_setprio(0); } while (0)
; #define PG8_WAIT_V(n) asm volatile("s_waitcnt vmcnt(" #n ")" ::: "memory")
; #define PG8_WAIT_L(n) asm volatile("s_waitcnt lgkmcnt(" #n ")" ::: "memory")
; #define PG8_BAR __builtin_amdgcn_s_barrier()
; #define PG8_SCHED __builtin_amdgcn_sched_barrier(0)
; template <class Epi, class Sched, bool ALIGN_EPI = false, bool SP2 = false>
; __device__ __forceinline__ void gemm_phase(PG8_LAS unsigned char* lds, const Gemm g, const Sched& S, const Epi& E) {
;     ...
;             PG8_LDA(At, 0, 1); PG8_STAGE(PG8_SB(0, 0), b2, voffB); PG8_STAGE(PG8_SB(0, 1), b2 + hstep, voffB); PG8_STAGE(PG8_SA(0, 0), a2, voffA);
;             PG8_WAIT_V(8); PG8_WAIT_L(0); PG8_BAR; PG8_MMA(1, 0, At, B0); PG8_MMA(1, 1, At, B1); PG8_BAR; PG8_SCHED;
;             PG8_LDB(B0, 1, 0); PG8_LDB(B1, 1, 1); PG8_SCHED; PG8_LDA(At, 1, 0); PG8_STAGE(PG8_SA(0, 1), a2 + hstepA, voffA);
	s_mov_b32 m0, s58
	s_nop 3
	ds_read_b128 v[72:75], v133 offset:16384
	ds_read_b128 v[76:79], v133 offset:17408
	ds_read_b128 v[80:83], v133 offset:18432
	ds_read_b128 v[84:87], v133 offset:19456
	ds_read_b128 v[88:91], v133 offset:20480
	ds_read_b128 v[92:95], v133 offset:21504
	ds_read_b128 v[112:115], v133 offset:22528
	ds_read_b128 v[116:119], v133 offset:23552
	global_load_lds_dwordx4 v[2:3], off
	s_mov_b32 m0, s53
	s_nop 0
	global_load_lds_dwordx4 v[4:5], off
	s_mov_b32 m0, s60
	s_nop 0
	global_load_lds_dwordx4 v[12:13], off
	s_mov_b32 m0, s59
	s_nop 0
	global_load_lds_dwordx4 v[14:15], off
	s_mov_b32 m0, s16
	s_nop 0
	global_load_lds_dwordx4 v[20:21], off
	s_mov_b32 m0, s52
	s_nop 0
	global_load_lds_dwordx4 v[28:29], off
	s_waitcnt vmcnt(8)
	s_waitcnt lgkmcnt(0)
	s_barrier
	s_setprio 1
	v_mfma_f32_16x16x32_bf16 v[2:5], v[154:157], v[72:75], v[190:193]
	v_mfma_f32_16x16x32_bf16 v[12:15], v[162:165], v[72:75], v[194:197]
	v_mfma_f32_16x16x32_bf16 v[26:29], v[154:157], v[80:83], v[198:201]
	v_mfma_f32_16x16x32_bf16 v[34:37], v[154:157], v[112:115], v[34:37]
	v_mfma_f32_16x16x32_bf16 v[38:41], v[162:165], v[112:115], v[38:41]
	v_mfma_f32_16x16x32_bf16 v[2:5], v[158:161], v[76:79], v[2:5]
	v_mfma_f32_16x16x32_bf16 v[12:15], v[178:181], v[76:79], v[12:15]
	v_mfma_f32_16x16x32_bf16 v[26:29], v[158:161], v[84:87], v[26:29]
	v_mfma_f32_16x16x32_bf16 v[190:193], v[162:165], v[80:83], v[202:205]
	v_mfma_f32_16x16x32_bf16 v[194:197], v[154:157], v[88:91], v[206:209]
	v_mfma_f32_16x16x32_bf16 v[198:201], v[162:165], v[88:91], v[210:213]
	v_mfma_f32_16x16x32_bf16 v[34:37], v[158:161], v[116:119], v[34:37]
	v_mfma_f32_16x16x32_bf16 v[38:41], v[178:181], v[116:119], v[38:41]
	v_mfma_f32_16x16x32_bf16 v[190:193], v[178:181], v[84:87], v[190:193]
	v_mfma_f32_16x16x32_bf16 v[194:197], v[158:161], v[92:95], v[194:197]
	v_mfma_f32_16x16x32_bf16 v[198:201], v[178:181], v[92:95], v[198:201]
	v_mfma_f32_16x16x32_bf16 v[42:45], v[182:185], v[72:75], v[42:45]
	v_mfma_f32_16x16x32_bf16 v[154:157], v[186:189], v[76:79], v[42:45]
	v_mfma_f32_16x16x32_bf16 v[42:45], v[214:217], v[72:75], v[46:49]
	v_mfma_f32_16x16x32_bf16 v[158:161], v[218:221], v[76:79], v[42:45]
	v_mfma_f32_16x16x32_bf16 v[42:45], v[182:185], v[80:83], v[60:63]
	v_mfma_f32_16x16x32_bf16 v[162:165], v[186:189], v[84:87], v[42:45]
	v_mfma_f32_16x16x32_bf16 v[42:45], v[214:217], v[80:83], v[64:67]
	v_mfma_f32_16x16x32_bf16 v[178:181], v[218:221], v[84:87], v[42:45]
	v_mfma_f32_16x16x32_bf16 v[42:45], v[182:185], v[88:91], v[96:99]
	v_mfma_f32_16x16x32_bf16 v[202:205], v[186:189], v[92:95], v[42:45]
	v_mfma_f32_16x16x32_bf16 v[42:45], v[214:217], v[88:91], v[144:147]
	v_mfma_f32_16x16x32_bf16 v[144:147], v[218:221], v[92:95], v[42:45]
	v_mfma_f32_16x16x32_bf16 v[42:45], v[182:185], v[112:115], v[50:53]
	v_mfma_f32_16x16x32_bf16 v[182:185], v[186:189], v[116:119], v[42:45]
	v_mfma_f32_16x16x32_bf16 v[42:45], v[214:217], v[112:115], v[54:57]
	v_mfma_f32_16x16x32_bf16 v[186:189], v[218:221], v[116:119], v[42:45]
	s_setprio 0
	s_barrier
	ds_read_b128 v[50:53], v135
	ds_read_b128 v[54:57], v135 offset:1024
	ds_read_b128 v[206:209], v135 offset:2048
	ds_read_b128 v[210:213], v135 offset:3072
	ds_read_b128 v[214:217], v177
	ds_read_b128 v[218:221], v177 offset:1024
	ds_read_b128 v[246:249], v177 offset:2048
	ds_read_b128 v[250:253], v177 offset:3072
	s_mov_b32 m0, s17
	ds_read_b128 v[42:45], v133 offset:32768
	ds_read_b128 v[46:49], v133 offset:33792
	ds_read_b128 v[58:61], v133 offset:34816
	ds_read_b128 v[62:65], v133 offset:35840
	ds_read_b128 v[94:97], v133 offset:36864
	ds_read_b128 v[6:9], v133 offset:37888
	ds_read_b128 v[72:75], v133 offset:38912
	ds_read_b128 v[76:79], v133 offset:39936
	global_load_lds_dwordx4 v[166:167], off
	s_mov_b32 m0, s28
	s_nop 0
	global_load_lds_dwordx4 v[10:11], off
	s_waitcnt vmcnt(8)
	s_waitcnt lgkmcnt(0)
	s_barrier
; #define PG8_STAGE(bufoff, gbase, voff) do { _Pragma("unroll") for (int _i = 0; _i < 2; ++_i) \
;         __builtin_amdgcn_global_load_lds((const unsigned*)((const char*)(gbase) + (voff)[_i]), (PG8_LAS unsigned*)(lds + (bufoff) + ldsw + _i * 8192), 16, 0, 0); } while (0)
; #define PG8_LDA(dst, b, h) do { _Pragma("unroll") for (int m = 0; m < 4; ++m) _Pragma("unroll") for (int k = 0; k < 2; ++k) dst[m][k] = *(const PG8_LAS bf16x8*)(lds + PG8_SA(b, h) + aoff + m * 2048 + k * 1024); } while (0)
; #define PG8_MMA(ai, bj, At, Bt) do { __builtin_amdgcn_s_setprio(1); _Pragma("unroll") for (int m = 0; m < 4; ++m) _Pragma("unroll") for (int n = 0; n < 2; ++n) _Pragma("unroll") for (int k = 0; k < 2; ++k) \
;         acc[ai][bj][m][n] = __builtin_amdgcn_mfma_f32_16x16x32_bf16(Bt[n][k], At[m][k], acc[ai][bj][m][n], 0, 0, 0); __builtin_amdgcn_s_setprio(0); } while (0)
; #define PG8_WAIT_V(n) asm volatile("s_waitcnt vmcnt(" #n ")" ::: "memory")
; #define PG8_WAIT_L(n) asm volatile("s_waitcnt lgkmcnt(" #n ")" ::: "memory")
; #define PG8_BAR __builtin_amdgcn_s_barrier()
; #define PG8_SCHED __builtin_amdgcn_sched_barrier(0)
; template <class Epi, class Sched, bool ALIGN_EPI = false, bool SP2 = false>
; __device__ __forceinline__ void gemm_phase(PG8_LAS unsigned char* lds, const Gemm g, const Sched& S, const Epi& E) {
;     ...
;             PG8_WAIT_V(8); PG8_WAIT_L(0); PG8_BAR; PG8_MMA(0, 0, At, B0); PG8_MMA(0, 1, At, B1); PG8_BAR; PG8_SCHED;
;             PG8_LDA(At, 1, 1); PG8_STAGE(PG8_SB(1, 0), b3, voffB); PG8_STAGE(PG8_SB(1, 1), b3 + hstep, voffB); PG8_STAGE(PG8_SA(1, 0), a3, voffA);
;             PG8_WAIT_V(8); PG8_WAIT_L(0); PG8_BAR; PG8_MMA(1, 0, At, B0); PG8_MMA(1, 1, At, B1); PG8_BAR; PG8_SCHED;
	s_setprio 1
	v_mfma_f32_16x16x32_bf16 v[80:83], v[50:53], v[42:45], v[100:103]
	v_mfma_f32_16x16x32_bf16 v[114:117], v[54:57], v[46:49], v[80:83]
	v_mfma_f32_16x16x32_bf16 v[80:83], v[206:209], v[42:45], v[104:107]
	v_mfma_f32_16x16x32_bf16 v[118:121], v[210:213], v[46:49], v[80:83]
	v_mfma_f32_16x16x32_bf16 v[80:83], v[50:53], v[58:61], v[108:111]
	v_mfma_f32_16x16x32_bf16 v[98:101], v[54:57], v[62:65], v[80:83]
	v_mfma_f32_16x16x32_bf16 v[80:83], v[206:209], v[58:61], v[170:173]
	v_mfma_f32_16x16x32_bf16 v[90:93], v[50:53], v[72:75], v[122:125]
	v_mfma_f32_16x16x32_bf16 v[102:105], v[210:213], v[62:65], v[80:83]
	v_mfma_f32_16x16x32_bf16 v[80:83], v[50:53], v[94:97], v[148:151]
	v_mfma_f32_16x16x32_bf16 v[86:89], v[206:209], v[94:97], v[128:131]
	v_mfma_f32_16x16x32_bf16 v[170:173], v[54:57], v[76:79], v[90:93]
	v_mfma_f32_16x16x32_bf16 v[90:93], v[206:209], v[72:75], v[136:139]
	v_mfma_f32_16x16x32_bf16 v[82:85], v[54:57], v[6:9], v[80:83]
	v_mfma_f32_16x16x32_bf16 v[86:89], v[210:213], v[6:9], v[86:89]
	v_mfma_f32_16x16x32_bf16 v[148:151], v[210:213], v[76:79], v[90:93]
	v_mfma_f32_16x16x32_bf16 v[90:93], v[214:217], v[42:45], v[140:143]
	v_mfma_f32_16x16x32_bf16 v[42:45], v[246:249], v[42:45], v[68:71]
	v_mfma_f32_16x16x32_bf16 v[126:129], v[250:253], v[46:49], v[42:45]
	v_mfma_f32_16x16x32_bf16 v[42:45], v[214:217], v[58:61], v[222:225]
	v_mfma_f32_16x16x32_bf16 v[106:109], v[218:221], v[62:65], v[42:45]
	v_mfma_f32_16x16x32_bf16 v[42:45], v[246:249], v[58:61], v[226:229]
	v_mfma_f32_16x16x32_bf16 v[110:113], v[250:253], v[62:65], v[42:45]
	v_mfma_f32_16x16x32_bf16 v[42:45], v[214:217], v[94:97], v[230:233]
	v_mfma_f32_16x16x32_bf16 v[122:125], v[218:221], v[46:49], v[90:93]
	v_mfma_f32_16x16x32_bf16 v[90:93], v[218:221], v[6:9], v[42:45]
	v_mfma_f32_16x16x32_bf16 v[42:45], v[246:249], v[94:97], v[234:237]
	v_mfma_f32_16x16x32_bf16 v[94:97], v[250:253], v[6:9], v[42:45]
	v_mfma_f32_16x16x32_bf16 v[6:9], v[214:217], v[72:75], v[238:241]
	v_mfma_f32_16x16x32_bf16 v[136:139], v[218:221], v[76:79], v[6:9]
	v_mfma_f32_16x16x32_bf16 v[6:9], v[246:249], v[72:75], v[242:245]
	v_mfma_f32_16x16x32_bf16 v[66:69], v[250:253], v[76:79], v[6:9]
	s_setprio 0
	s_barrier
	s_mov_b32 m0, s30
	s_nop 3
	ds_read_b128 v[6:9], v133 offset:49152
	ds_read_b128 v[70:73], v133 offset:50176
	ds_read_b128 v[74:77], v133 offset:51200
	ds_read_b128 v[78:81], v133 offset:52224
	ds_read_b128 v[140:143], v133 offset:53248
	ds_read_b128 v[222:225], v133 offset:54272
	ds_read_b128 v[226:229], v133 offset:55296
	ds_read_b128 v[230:233], v133 offset:56320
	global_load_lds_dwordx4 v[18:19], off
	s_mov_b32 m0, s46
	s_nop 0
	global_load_lds_dwordx4 v[22:23], off
	s_mov_b32 m0, s50
	s_nop 0
	global_load_lds_dwordx4 v[30:31], off
	s_mov_b32 m0, s51
	s_nop 0
	global_load_lds_dwordx4 v[32:33], off
	s_mov_b32 m0, s35
	s_nop 0
	global_load_lds_dwordx4 v[16:17], off
	s_mov_b32 m0, s47
	s_nop 0
	global_load_lds_dwordx4 v[24:25], off
	s_waitcnt vmcnt(8)
	s_waitcnt lgkmcnt(0)
	s_barrier
	s_setprio 1
	v_mfma_f32_16x16x32_bf16 v[2:5], v[50:53], v[6:9], v[2:5]
	v_mfma_f32_16x16x32_bf16 v[62:65], v[54:57], v[70:73], v[2:5]
	v_mfma_f32_16x16x32_bf16 v[2:5], v[206:209], v[6:9], v[12:15]
	v_mfma_f32_16x16x32_bf16 v[58:61], v[210:213], v[70:73], v[2:5]
	v_mfma_f32_16x16x32_bf16 v[2:5], v[50:53], v[74:77], v[26:29]
	v_mfma_f32_16x16x32_bf16 v[46:49], v[54:57], v[78:81], v[2:5]
	v_mfma_f32_16x16x32_bf16 v[2:5], v[206:209], v[74:77], v[190:193]
	v_mfma_f32_16x16x32_bf16 v[42:45], v[210:213], v[78:81], v[2:5]
	v_mfma_f32_16x16x32_bf16 v[2:5], v[50:53], v[140:143], v[194:197]
	v_mfma_f32_16x16x32_bf16 v[30:33], v[54:57], v[222:225], v[2:5]
	v_mfma_f32_16x16x32_bf16 v[2:5], v[206:209], v[140:143], v[198:201]
	v_mfma_f32_16x16x32_bf16 v[26:29], v[210:213], v[222:225], v[2:5]
	v_mfma_f32_16x16x32_bf16 v[2:5], v[50:53], v[226:229], v[34:37]
	v_mfma_f32_16x16x32_bf16 v[14:17], v[54:57], v[230:233], v[2:5]
	v_mfma_f32_16x16x32_bf16 v[2:5], v[206:209], v[226:229], v[38:41]
	v_mfma_f32_16x16x32_bf16 v[10:13], v[210:213], v[230:233], v[2:5]
	v_mfma_f32_16x16x32_bf16 v[2:5], v[214:217], v[6:9], v[154:157]
	v_mfma_f32_16x16x32_bf16 v[54:57], v[218:221], v[70:73], v[2:5]
	v_mfma_f32_16x16x32_bf16 v[2:5], v[246:249], v[6:9], v[158:161]
	v_mfma_f32_16x16x32_bf16 v[50:53], v[250:253], v[70:73], v[2:5]
	v_mfma_f32_16x16x32_bf16 v[2:5], v[214:217], v[74:77], v[162:165]
	v_mfma_f32_16x16x32_bf16 v[38:41], v[218:221], v[78:81], v[2:5]
	v_mfma_f32_16x16x32_bf16 v[2:5], v[246:249], v[74:77], v[178:181]
	v_mfma_f32_16x16x32_bf16 v[34:37], v[250:253], v[78:81], v[2:5]
	v_mfma_f32_16x16x32_bf16 v[2:5], v[214:217], v[140:143], v[202:205]
	v_mfma_f32_16x16x32_bf16 v[22:25], v[218:221], v[222:225], v[2:5]
	v_mfma_f32_16x16x32_bf16 v[2:5], v[246:249], v[140:143], v[144:147]
	v_mfma_f32_16x16x32_bf16 v[18:21], v[250:253], v[222:225], v[2:5]
	v_mfma_f32_16x16x32_bf16 v[2:5], v[214:217], v[226:229], v[182:185]
	v_mfma_f32_16x16x32_bf16 v[6:9], v[218:221], v[230:233], v[2:5]
	v_mfma_f32_16x16x32_bf16 v[2:5], v[246:249], v[226:229], v[186:189]
	v_mfma_f32_16x16x32_bf16 v[2:5], v[250:253], v[230:233], v[2:5]
	s_setprio 0
	s_barrier
	s_cbranch_scc1 .LBB0_419
	s_barrier
